# LN2 also stores only per-row mean/rstd; FFN-out writes its raw rows to the X buffer and the next layer's out-proj epilogue rebuilds the LN2 residual from them (same f32 ops)
# speedup vs baseline: 1.0099x; 1.0044x over previous
.LBB0_53:
	s_mul_i32 s10, s9, 0x5000
	v_add_u32_e32 v156, s10, v142
	v_lshl_add_u64 v[126:127], v[124:125], 0, s[0:1]
	v_readfirstlane_b32 s10, v156
	v_add_u32_e32 v136, 0x1000, v156
	v_lshl_add_u64 v[134:135], v[126:127], 0, s[2:3]
	s_mov_b32 m0, s10
	v_lshl_add_u64 v[138:139], v[122:123], 0, s[0:1]
	v_readfirstlane_b32 s10, v136
	s_waitcnt vmcnt(5)
	s_barrier
	global_load_lds_dwordx4 v[134:135], off
	v_lshl_add_u64 v[134:135], v[138:139], 0, s[2:3]
	s_mov_b32 m0, s10
	v_add_u32_e32 v140, 0x2000, v156
	global_load_lds_dwordx4 v[134:135], off
	v_lshl_add_u64 v[134:135], v[120:121], 0, s[0:1]
	v_readfirstlane_b32 s10, v140
	v_lshl_add_u64 v[136:137], v[134:135], 0, s[2:3]
	s_mov_b32 m0, s10
	v_add_u32_e32 v154, 0x3000, v156
	global_load_lds_dwordx4 v[136:137], off
	v_lshl_add_u64 v[136:137], v[118:119], 0, s[0:1]
	v_readfirstlane_b32 s10, v154
	v_lshl_add_u64 v[140:141], v[136:137], 0, s[2:3]
	s_mov_b32 m0, s10
	v_add_u32_e32 v156, 0x4000, v156
	global_load_lds_dwordx4 v[140:141], off
	v_lshl_add_u64 v[140:141], v[116:117], 0, s[0:1]
	v_readfirstlane_b32 s10, v156
	v_lshl_add_u64 v[154:155], v[140:141], 0, s[2:3]
	s_mov_b32 m0, s10
	s_mul_i32 s10, s8, 0x5000
	global_load_lds_dwordx4 v[154:155], off
	v_or_b32_e32 v154, s10, v147
	v_add_u32_e32 v170, v154, v128
	ds_read_b128 v[154:157], v170
	ds_read_b128 v[158:161], v170 offset:1024
	ds_read_b128 v[162:165], v170 offset:2048
	ds_read_b128 v[166:169], v170 offset:3072
	ds_read_b128 v[200:203], v170 offset:4096
	ds_read_b128 v[204:207], v170 offset:5120
	v_or_b32_e32 v170, s10, v149
	v_add_u32_e32 v170, v170, v148
	s_add_i32 s8, s8, 1
	s_add_i32 s9, s9, 1
	ds_read_b128 v[208:211], v170 offset:12288
	ds_read_b128 v[212:215], v170 offset:13312
	ds_read_b128 v[216:219], v170 offset:14336
	ds_read_b128 v[220:223], v170 offset:15360
	s_cmp_lg_u32 s8, 3
	s_cselect_b32 s8, s8, 0
	s_cmp_lg_u32 s9, 3
	s_cselect_b32 s9, s9, 0
	s_mul_i32 s10, s9, 0x5000
	s_waitcnt lgkmcnt(0)
	v_mfma_f32_16x16x32_bf16 v[92:95], v[208:211], v[154:157], v[92:95]
	v_lshl_add_u64 v[126:127], v[126:127], 0, s[30:31]
	s_waitcnt vmcnt(5)
	s_barrier
	v_mfma_f32_16x16x32_bf16 v[88:91], v[212:215], v[154:157], v[88:91]
	s_add_i32 s9, s9, 1
	v_mfma_f32_16x16x32_bf16 v[84:87], v[216:219], v[154:157], v[84:87]
	v_mfma_f32_16x16x32_bf16 v[80:83], v[220:223], v[154:157], v[80:83]
	v_add_u32_e32 v154, s10, v142
	s_nop 0
	v_readfirstlane_b32 s10, v154
	s_mov_b32 m0, s10
	v_mfma_f32_16x16x32_bf16 v[76:79], v[208:211], v[158:161], v[76:79]
	global_load_lds_dwordx4 v[126:127], off
	v_lshl_add_u64 v[126:127], v[138:139], 0, s[30:31]
	v_add_u32_e32 v138, 0x1000, v154
	v_mfma_f32_16x16x32_bf16 v[72:75], v[212:215], v[158:161], v[72:75]
	v_readfirstlane_b32 s10, v138
	s_mov_b32 m0, s10
	s_nop 0
	global_load_lds_dwordx4 v[126:127], off
	v_lshl_add_u64 v[126:127], v[134:135], 0, s[30:31]
	v_add_u32_e32 v134, 0x2000, v154
	v_mfma_f32_16x16x32_bf16 v[68:71], v[216:219], v[158:161], v[68:71]
	v_readfirstlane_b32 s10, v134
	v_add_u32_e32 v134, 0x3000, v154
	s_mov_b32 m0, s10
	v_readfirstlane_b32 s10, v134
	v_add_u32_e32 v134, 0x4000, v154
	global_load_lds_dwordx4 v[126:127], off
	v_lshl_add_u64 v[126:127], v[136:137], 0, s[30:31]
	s_mov_b32 m0, s10
	v_readfirstlane_b32 s10, v134
	global_load_lds_dwordx4 v[126:127], off
	v_lshl_add_u64 v[126:127], v[140:141], 0, s[30:31]
	s_mov_b32 m0, s10
	s_mul_i32 s10, s8, 0x5000
	global_load_lds_dwordx4 v[126:127], off
	v_or_b32_e32 v126, s10, v147
	v_add_u32_e32 v126, v126, v128
	v_mfma_f32_16x16x32_bf16 v[64:67], v[220:223], v[158:161], v[64:67]
	s_add_i32 s8, s8, 1
	s_cmp_lg_u32 s8, 3
	s_cselect_b32 s8, s8, 0
	v_mfma_f32_16x16x32_bf16 v[60:63], v[208:211], v[162:165], v[60:63]
	s_cmp_lg_u32 s9, 3
	s_cselect_b32 s9, s9, 0
	s_add_u32 s0, s0, 0x80
	v_mfma_f32_16x16x32_bf16 v[56:59], v[212:215], v[162:165], v[56:59]
	s_addc_u32 s1, s1, 0
	s_cmpk_eq_i32 s0, 0x1580
	v_mfma_f32_16x16x32_bf16 v[52:55], v[216:219], v[162:165], v[52:55]
	v_mfma_f32_16x16x32_bf16 v[48:51], v[220:223], v[162:165], v[48:51]
	v_mfma_f32_16x16x32_bf16 v[44:47], v[208:211], v[166:169], v[44:47]
	v_mfma_f32_16x16x32_bf16 v[40:43], v[212:215], v[166:169], v[40:43]
	v_mfma_f32_16x16x32_bf16 v[36:39], v[216:219], v[166:169], v[36:39]
	v_mfma_f32_16x16x32_bf16 v[32:35], v[220:223], v[166:169], v[32:35]
	ds_read_b128 v[134:137], v126
	ds_read_b128 v[138:141], v126 offset:1024
	ds_read_b128 v[154:157], v126 offset:2048
	ds_read_b128 v[158:161], v126 offset:3072
	ds_read_b128 v[162:165], v126 offset:4096
	ds_read_b128 v[166:169], v126 offset:5120
	v_or_b32_e32 v126, s10, v149
	v_add_u32_e32 v126, v126, v148
	v_mfma_f32_16x16x32_bf16 v[28:31], v[208:211], v[200:203], v[28:31]
	v_mfma_f32_16x16x32_bf16 v[24:27], v[212:215], v[200:203], v[24:27]
	v_mfma_f32_16x16x32_bf16 v[20:23], v[216:219], v[200:203], v[20:23]
	v_mfma_f32_16x16x32_bf16 v[16:19], v[220:223], v[200:203], v[16:19]
	v_mfma_f32_16x16x32_bf16 v[8:11], v[208:211], v[204:207], v[8:11]
	v_mfma_f32_16x16x32_bf16 v[4:7], v[212:215], v[204:207], v[4:7]
	v_mfma_f32_16x16x32_bf16 v[12:15], v[216:219], v[204:207], v[12:15]
	v_mfma_f32_16x16x32_bf16 v[0:3], v[220:223], v[204:207], v[0:3]
	ds_read_b128 v[200:203], v126 offset:12288
	ds_read_b128 v[204:207], v126 offset:13312
	ds_read_b128 v[208:211], v126 offset:14336
	ds_read_b128 v[212:215], v126 offset:15360
	s_waitcnt lgkmcnt(0)
	v_mfma_f32_16x16x32_bf16 v[92:95], v[200:203], v[134:137], v[92:95]
	v_mfma_f32_16x16x32_bf16 v[88:91], v[204:207], v[134:137], v[88:91]
	v_mfma_f32_16x16x32_bf16 v[84:87], v[208:211], v[134:137], v[84:87]
	v_mfma_f32_16x16x32_bf16 v[80:83], v[212:215], v[134:137], v[80:83]
	v_mfma_f32_16x16x32_bf16 v[76:79], v[200:203], v[138:141], v[76:79]
	v_mfma_f32_16x16x32_bf16 v[72:75], v[204:207], v[138:141], v[72:75]
	v_mfma_f32_16x16x32_bf16 v[68:71], v[208:211], v[138:141], v[68:71]
	v_mfma_f32_16x16x32_bf16 v[64:67], v[212:215], v[138:141], v[64:67]
	v_mfma_f32_16x16x32_bf16 v[60:63], v[200:203], v[154:157], v[60:63]
	v_mfma_f32_16x16x32_bf16 v[56:59], v[204:207], v[154:157], v[56:59]
	v_mfma_f32_16x16x32_bf16 v[52:55], v[208:211], v[154:157], v[52:55]
	v_mfma_f32_16x16x32_bf16 v[48:51], v[212:215], v[154:157], v[48:51]
	v_mfma_f32_16x16x32_bf16 v[44:47], v[200:203], v[158:161], v[44:47]
	v_mfma_f32_16x16x32_bf16 v[40:43], v[204:207], v[158:161], v[40:43]
	v_mfma_f32_16x16x32_bf16 v[36:39], v[208:211], v[158:161], v[36:39]
	v_mfma_f32_16x16x32_bf16 v[32:35], v[212:215], v[158:161], v[32:35]
	v_mfma_f32_16x16x32_bf16 v[28:31], v[200:203], v[162:165], v[28:31]
	v_mfma_f32_16x16x32_bf16 v[24:27], v[204:207], v[162:165], v[24:27]
	v_mfma_f32_16x16x32_bf16 v[20:23], v[208:211], v[162:165], v[20:23]
	v_mfma_f32_16x16x32_bf16 v[16:19], v[212:215], v[162:165], v[16:19]
	v_mfma_f32_16x16x32_bf16 v[8:11], v[200:203], v[166:169], v[8:11]
	v_mfma_f32_16x16x32_bf16 v[4:7], v[204:207], v[166:169], v[4:7]
	v_mfma_f32_16x16x32_bf16 v[12:15], v[208:211], v[166:169], v[12:15]
	v_mfma_f32_16x16x32_bf16 v[0:3], v[212:215], v[166:169], v[0:3]
	s_cbranch_scc0 .LBB0_53
	v_add_u32_e32 v170, v147, v128
	v_add_u32_e32 v172, v149, v148
	s_waitcnt vmcnt(5)
	s_barrier
	ds_read_b128 v[116:119], v170 offset:40960
	ds_read_b128 v[120:123], v170 offset:41984
	ds_read_b128 v[124:127], v170 offset:43008
	ds_read_b128 v[134:137], v170 offset:44032
	ds_read_b128 v[138:141], v170 offset:45056
	ds_read_b128 v[154:157], v170 offset:46080
	ds_read_b128 v[158:161], v172 offset:53248
	ds_read_b128 v[162:165], v172 offset:54272
	ds_read_b128 v[166:169], v172 offset:55296
	ds_read_b128 v[200:203], v172 offset:56320
	s_waitcnt lgkmcnt(0)
	v_mfma_f32_16x16x32_bf16 v[92:95], v[158:161], v[116:119], v[92:95]
	s_waitcnt vmcnt(0)
	s_barrier
	s_mulk_i32 s7, 0xc0
	v_mfma_f32_16x16x32_bf16 v[88:91], v[162:165], v[116:119], v[88:91]
	v_readlane_b32 s8, v243, 5
	v_readlane_b32 s14, v243, 11
	v_readlane_b32 s15, v243, 12
	v_mfma_f32_16x16x32_bf16 v[84:87], v[166:169], v[116:119], v[84:87]
	v_readlane_b32 s9, v243, 6
	v_readlane_b32 s10, v243, 7
	v_readlane_b32 s11, v243, 8
	v_mfma_f32_16x16x32_bf16 v[80:83], v[200:203], v[116:119], v[80:83]
	v_readlane_b32 s12, v243, 9
	v_readlane_b32 s13, v243, 10
	v_readlane_b32 s16, v243, 13
	v_mfma_f32_16x16x32_bf16 v[76:79], v[158:161], v[120:123], v[76:79]
	v_readlane_b32 s17, v243, 14
	v_readlane_b32 s18, v243, 15
	v_readlane_b32 s19, v243, 16
	v_mfma_f32_16x16x32_bf16 v[72:75], v[162:165], v[120:123], v[72:75]
	v_readlane_b32 s20, v243, 17
	v_readlane_b32 s21, v243, 18
	v_readlane_b32 s22, v243, 19
	v_mfma_f32_16x16x32_bf16 v[68:71], v[166:169], v[120:123], v[68:71]
	v_readlane_b32 s23, v243, 20
	s_mov_b64 s[24:25], 0x5000
	s_add_i32 s5, s5, s51
	v_mfma_f32_16x16x32_bf16 v[64:67], v[200:203], v[120:123], v[64:67]
	s_cmpk_gt_i32 s5, 0xff
	v_mfma_f32_16x16x32_bf16 v[60:63], v[158:161], v[124:127], v[60:63]
	v_mfma_f32_16x16x32_bf16 v[56:59], v[162:165], v[124:127], v[56:59]
	v_mfma_f32_16x16x32_bf16 v[52:55], v[166:169], v[124:127], v[52:55]
	v_mfma_f32_16x16x32_bf16 v[48:51], v[200:203], v[124:127], v[48:51]
	v_mfma_f32_16x16x32_bf16 v[44:47], v[158:161], v[134:137], v[44:47]
	v_mfma_f32_16x16x32_bf16 v[40:43], v[162:165], v[134:137], v[40:43]
	v_mfma_f32_16x16x32_bf16 v[36:39], v[166:169], v[134:137], v[36:39]
	v_mfma_f32_16x16x32_bf16 v[32:35], v[200:203], v[134:137], v[32:35]
	v_mfma_f32_16x16x32_bf16 v[28:31], v[158:161], v[138:141], v[28:31]
	v_mfma_f32_16x16x32_bf16 v[24:27], v[162:165], v[138:141], v[24:27]
	v_mfma_f32_16x16x32_bf16 v[20:23], v[166:169], v[138:141], v[20:23]
	v_mfma_f32_16x16x32_bf16 v[16:19], v[200:203], v[138:141], v[16:19]
	v_mfma_f32_16x16x32_bf16 v[8:11], v[158:161], v[154:157], v[8:11]
	v_mfma_f32_16x16x32_bf16 v[4:7], v[162:165], v[154:157], v[4:7]
	v_mfma_f32_16x16x32_bf16 v[116:119], v[166:169], v[154:157], v[12:15]
	v_mfma_f32_16x16x32_bf16 v[0:3], v[200:203], v[154:157], v[0:3]
	s_nop 1
	ds_read_b128 v[12:15], v170
	ds_read_b128 v[120:123], v170 offset:1024
	ds_read_b128 v[124:127], v170 offset:2048
	ds_read_b128 v[134:137], v170 offset:3072
	ds_read_b128 v[138:141], v170 offset:4096
	ds_read_b128 v[154:157], v170 offset:5120
	ds_read_b128 v[158:161], v172 offset:12288
	ds_read_b128 v[162:165], v172 offset:13312
	ds_read_b128 v[166:169], v172 offset:14336
	ds_read_b128 v[200:203], v172 offset:15360
	s_waitcnt lgkmcnt(0)
	v_mfma_f32_16x16x32_bf16 v[76:79], v[158:161], v[120:123], v[76:79]
	v_mfma_f32_16x16x32_bf16 v[72:75], v[162:165], v[120:123], v[72:75]
	v_mfma_f32_16x16x32_bf16 v[68:71], v[166:169], v[120:123], v[68:71]
	v_mfma_f32_16x16x32_bf16 v[64:67], v[200:203], v[120:123], v[64:67]
	v_mfma_f32_16x16x32_bf16 v[204:207], v[158:161], v[12:15], v[92:95]
	v_mfma_f32_16x16x32_bf16 v[88:91], v[162:165], v[12:15], v[88:91]
	v_mfma_f32_16x16x32_bf16 v[84:87], v[166:169], v[12:15], v[84:87]
	v_mfma_f32_16x16x32_bf16 v[80:83], v[200:203], v[12:15], v[80:83]
	v_mfma_f32_16x16x32_bf16 v[12:15], v[158:161], v[154:157], v[8:11]
	v_mfma_f32_16x16x32_bf16 v[8:11], v[162:165], v[154:157], v[4:7]
	v_mfma_f32_16x16x32_bf16 v[4:7], v[166:169], v[154:157], v[116:119]
	v_mfma_f32_16x16x32_bf16 v[28:31], v[158:161], v[138:141], v[28:31]
	v_mfma_f32_16x16x32_bf16 v[24:27], v[162:165], v[138:141], v[24:27]
	v_mfma_f32_16x16x32_bf16 v[20:23], v[166:169], v[138:141], v[20:23]
	v_mfma_f32_16x16x32_bf16 v[16:19], v[200:203], v[138:141], v[16:19]
	v_mfma_f32_16x16x32_bf16 v[60:63], v[158:161], v[124:127], v[60:63]
	v_mfma_f32_16x16x32_bf16 v[56:59], v[162:165], v[124:127], v[56:59]
	v_mfma_f32_16x16x32_bf16 v[52:55], v[166:169], v[124:127], v[52:55]
	v_mfma_f32_16x16x32_bf16 v[48:51], v[200:203], v[124:127], v[48:51]
	v_mfma_f32_16x16x32_bf16 v[44:47], v[158:161], v[134:137], v[44:47]
	v_mfma_f32_16x16x32_bf16 v[40:43], v[162:165], v[134:137], v[40:43]
	v_mfma_f32_16x16x32_bf16 v[36:39], v[166:169], v[134:137], v[36:39]
	v_mfma_f32_16x16x32_bf16 v[32:35], v[200:203], v[134:137], v[32:35]
	v_mfma_f32_16x16x32_bf16 v[0:3], v[200:203], v[154:157], v[0:3]
	v_readlane_b32 s10, v242, 27
	v_readlane_b32 s11, v242, 28
	v_readlane_b32 s12, v242, 25
	v_readlane_b32 s13, v242, 26
	v_readlane_b32 s14, v243, 11
	v_readlane_b32 s15, v243, 12
	s_mov_b32 s8, 0x3fd744fd
	v_add_u32_e32 v236, s7, v145
	v_or_b32_e32 v254, s6, v146
	v_mov_b32_e32 v255, 0
	v_or_b32_e32 v237, v236, v133
	v_lshlrev_b64 v[254:255], 2, v[254:255]
	s_nop 0
	v_lshl_add_u64 v[250:251], s[12:13], 0, v[254:255]
	v_lshl_add_u64 v[252:253], s[14:15], 0, v[254:255]
	s_mov_b64 s[14:15], 0x5000
	v_lshl_add_u64 v[252:253], v[252:253], 0, s[14:15]
	v_readlane_b32 s12, v242, 29
	v_readlane_b32 s13, v242, 30
	v_lshl_add_u64 v[248:249], s[12:13], 0, v[254:255]
	v_readlane_b32 s12, v241, 9
	s_add_i32 s12, s12, -10
	s_mul_i32 s12, s12, 57
	s_lshr_b32 s12, s12, 9
	s_lshl_b32 s12, s12, 12
	v_readlane_b32 s14, v243, 59
	v_readlane_b32 s15, v243, 60
	s_add_u32 s14, s14, s12
	s_addc_u32 s15, s15, 0
	v_lshl_add_u64 v[224:225], s[14:15], 0, v[254:255]
	v_readlane_b32 s14, v243, 61
	v_readlane_b32 s15, v243, 62
	s_add_u32 s14, s14, s12
	s_addc_u32 s15, s15, 0
	v_lshl_add_u64 v[226:227], s[14:15], 0, v[254:255]
	global_load_dwordx4 v[96:99], v[224:225], off
	global_load_dwordx4 v[112:115], v[226:227], off
	global_load_dwordx4 v[100:103], v[224:225], off offset:64
	global_load_dwordx4 v[150:153], v[226:227], off offset:64
	global_load_dwordx4 v[104:107], v[224:225], off offset:128
	global_load_dwordx4 v[142:145], v[226:227], off offset:128
	global_load_dwordx4 v[108:111], v[224:225], off offset:192
	global_load_dwordx4 v[146:149], v[226:227], off offset:192
	v_mov_b32_e32 v255, 0
	v_add_u32_e32 v254, 0, v237
	v_add_u32_e32 v236, 0xfffff000, v254
	v_cmp_lt_i32_e32 vcc, 0xfff, v254
	v_lshrrev_b32_e32 v236, 10, v236
	v_lshlrev_b32_e32 v224, 3, v254
	v_lshlrev_b32_e32 v254, 12, v254
	v_add_u32_e32 v236, 1, v236
	v_mov_b32_e32 v225, 0
	v_cndmask_b32_e32 v236, 0, v236, vcc
	v_lshl_add_u64 v[224:225], v[224:225], 0, s[10:11]
	v_lshl_add_u64 v[228:229], v[254:255], 0, v[250:251]
	v_add_u32_e32 v236, s4, v236
	v_mad_i64_i32 v[232:233], s[0:1], v236, s33, v[252:253]
	global_load_dwordx2 v[132:133], v[224:225], off
	v_lshl_add_u64 v[224:225], v[254:255], 0, v[248:249]
	v_add_u32_e32 v254, 16, v237
	v_add_u32_e32 v236, 0xfffff000, v254
	v_cmp_lt_i32_e32 vcc, 0xfff, v254
	v_lshrrev_b32_e32 v236, 10, v236
	v_lshlrev_b32_e32 v226, 3, v254
	v_lshlrev_b32_e32 v254, 12, v254
	v_add_u32_e32 v236, 1, v236
	v_mov_b32_e32 v227, 0
	v_cndmask_b32_e32 v236, 0, v236, vcc
	v_lshl_add_u64 v[226:227], v[226:227], 0, s[10:11]
	v_lshl_add_u64 v[230:231], v[254:255], 0, v[250:251]
	v_add_u32_e32 v236, s4, v236
	v_mad_i64_i32 v[234:235], s[0:1], v236, s33, v[252:253]
	global_load_dword v128, v[226:227], off
	global_load_dword v170, v[226:227], off offset:4
	v_lshl_add_u64 v[226:227], v[254:255], 0, v[248:249]
	global_load_dwordx4 v[154:157], v[224:225], off
	global_load_dwordx4 v[116:119], v[232:233], off
	global_load_dwordx4 v[158:161], v[224:225], off offset:64
	global_load_dwordx4 v[120:123], v[232:233], off offset:64
	global_load_dwordx4 v[162:165], v[224:225], off offset:128
	global_load_dwordx4 v[124:127], v[232:233], off offset:128
	global_load_dwordx4 v[166:169], v[224:225], off offset:192
	global_load_dwordx4 v[134:137], v[232:233], off offset:192
	global_load_dwordx4 v[208:211], v[226:227], off
	global_load_dwordx4 v[138:141], v[234:235], off
	global_load_dwordx4 v[212:215], v[226:227], off offset:64
	global_load_dwordx4 v[200:203], v[234:235], off offset:64
	global_load_dwordx4 v[216:219], v[226:227], off offset:128
	global_load_dwordx4 v[92:95], v[234:235], off offset:128
	global_load_dwordx4 v[220:223], v[226:227], off offset:192
	global_load_dwordx4 v[244:247], v[234:235], off offset:192
	s_waitcnt vmcnt(0)
	v_pk_mul_f32 v[204:205], v[204:205], v[116:117]
	v_pk_add_f32 v[154:155], v[154:155], v[132:133] op_sel_hi:[1,0] neg_lo:[0,1] neg_hi:[0,1]
	v_pk_mul_f32 v[206:207], v[206:207], v[118:119]
	v_pk_add_f32 v[156:157], v[156:157], v[132:133] op_sel_hi:[1,0] neg_lo:[0,1] neg_hi:[0,1]
	v_pk_mul_f32 v[154:155], v[154:155], v[132:133] op_sel:[0,1] op_sel_hi:[1,1]
	v_pk_mul_f32 v[156:157], v[156:157], v[132:133] op_sel:[0,1] op_sel_hi:[1,1]
	v_pk_fma_f32 v[154:155], v[96:97], v[154:155], v[112:113]
	v_pk_fma_f32 v[156:157], v[98:99], v[156:157], v[114:115]
	v_pk_fma_f32 v[204:205], v[154:155], s[8:9], v[204:205] op_sel_hi:[1,0,1]
	v_pk_fma_f32 v[206:207], v[156:157], s[8:9], v[206:207] op_sel_hi:[1,0,1]
	global_store_dwordx4 v[228:229], v[204:207], off
	v_pk_mul_f32 v[88:89], v[88:89], v[120:121]
	v_pk_add_f32 v[158:159], v[158:159], v[132:133] op_sel_hi:[1,0] neg_lo:[0,1] neg_hi:[0,1]
	v_pk_mul_f32 v[90:91], v[90:91], v[122:123]
	v_pk_add_f32 v[160:161], v[160:161], v[132:133] op_sel_hi:[1,0] neg_lo:[0,1] neg_hi:[0,1]
	v_pk_mul_f32 v[158:159], v[158:159], v[132:133] op_sel:[0,1] op_sel_hi:[1,1]
	v_pk_mul_f32 v[160:161], v[160:161], v[132:133] op_sel:[0,1] op_sel_hi:[1,1]
	v_pk_fma_f32 v[158:159], v[100:101], v[158:159], v[150:151]
	v_pk_fma_f32 v[160:161], v[102:103], v[160:161], v[152:153]
	v_pk_fma_f32 v[88:89], v[158:159], s[8:9], v[88:89] op_sel_hi:[1,0,1]
	v_pk_fma_f32 v[90:91], v[160:161], s[8:9], v[90:91] op_sel_hi:[1,0,1]
	global_store_dwordx4 v[228:229], v[88:91], off offset:64
	v_pk_mul_f32 v[84:85], v[84:85], v[124:125]
	v_pk_add_f32 v[162:163], v[162:163], v[132:133] op_sel_hi:[1,0] neg_lo:[0,1] neg_hi:[0,1]
	v_pk_mul_f32 v[86:87], v[86:87], v[126:127]
	v_pk_add_f32 v[164:165], v[164:165], v[132:133] op_sel_hi:[1,0] neg_lo:[0,1] neg_hi:[0,1]
	v_pk_mul_f32 v[162:163], v[162:163], v[132:133] op_sel:[0,1] op_sel_hi:[1,1]
	v_pk_mul_f32 v[164:165], v[164:165], v[132:133] op_sel:[0,1] op_sel_hi:[1,1]
	v_pk_fma_f32 v[162:163], v[104:105], v[162:163], v[142:143]
	v_pk_fma_f32 v[164:165], v[106:107], v[164:165], v[144:145]
	v_pk_fma_f32 v[84:85], v[162:163], s[8:9], v[84:85] op_sel_hi:[1,0,1]
	v_pk_fma_f32 v[86:87], v[164:165], s[8:9], v[86:87] op_sel_hi:[1,0,1]
	global_store_dwordx4 v[228:229], v[84:87], off offset:128
	v_pk_mul_f32 v[80:81], v[80:81], v[134:135]
	v_pk_add_f32 v[166:167], v[166:167], v[132:133] op_sel_hi:[1,0] neg_lo:[0,1] neg_hi:[0,1]
	v_pk_mul_f32 v[82:83], v[82:83], v[136:137]
	v_pk_add_f32 v[168:169], v[168:169], v[132:133] op_sel_hi:[1,0] neg_lo:[0,1] neg_hi:[0,1]
	v_pk_mul_f32 v[166:167], v[166:167], v[132:133] op_sel:[0,1] op_sel_hi:[1,1]
	v_pk_mul_f32 v[168:169], v[168:169], v[132:133] op_sel:[0,1] op_sel_hi:[1,1]
	v_pk_fma_f32 v[166:167], v[108:109], v[166:167], v[146:147]
	v_pk_fma_f32 v[168:169], v[110:111], v[168:169], v[148:149]
	v_pk_fma_f32 v[80:81], v[166:167], s[8:9], v[80:81] op_sel_hi:[1,0,1]
	v_pk_fma_f32 v[82:83], v[168:169], s[8:9], v[82:83] op_sel_hi:[1,0,1]
	global_store_dwordx4 v[228:229], v[80:83], off offset:192
	v_pk_mul_f32 v[76:77], v[76:77], v[138:139]
	v_pk_add_f32 v[208:209], v[208:209], v[128:129] op_sel_hi:[1,0] neg_lo:[0,1] neg_hi:[0,1]
	v_pk_mul_f32 v[78:79], v[78:79], v[140:141]
	v_pk_add_f32 v[210:211], v[210:211], v[128:129] op_sel_hi:[1,0] neg_lo:[0,1] neg_hi:[0,1]
	v_pk_mul_f32 v[208:209], v[208:209], v[170:171] op_sel_hi:[1,0]
	v_pk_mul_f32 v[210:211], v[210:211], v[170:171] op_sel_hi:[1,0]
	v_pk_fma_f32 v[208:209], v[96:97], v[208:209], v[112:113]
	v_pk_fma_f32 v[210:211], v[98:99], v[210:211], v[114:115]
	v_pk_fma_f32 v[76:77], v[208:209], s[8:9], v[76:77] op_sel_hi:[1,0,1]
	v_pk_fma_f32 v[78:79], v[210:211], s[8:9], v[78:79] op_sel_hi:[1,0,1]
	global_store_dwordx4 v[230:231], v[76:79], off
	v_pk_mul_f32 v[72:73], v[72:73], v[200:201]
	v_pk_add_f32 v[212:213], v[212:213], v[128:129] op_sel_hi:[1,0] neg_lo:[0,1] neg_hi:[0,1]
	v_pk_mul_f32 v[74:75], v[74:75], v[202:203]
	v_pk_add_f32 v[214:215], v[214:215], v[128:129] op_sel_hi:[1,0] neg_lo:[0,1] neg_hi:[0,1]
	v_pk_mul_f32 v[212:213], v[212:213], v[170:171] op_sel_hi:[1,0]
	v_pk_mul_f32 v[214:215], v[214:215], v[170:171] op_sel_hi:[1,0]
	v_pk_fma_f32 v[212:213], v[100:101], v[212:213], v[150:151]
	v_pk_fma_f32 v[214:215], v[102:103], v[214:215], v[152:153]
	v_pk_fma_f32 v[72:73], v[212:213], s[8:9], v[72:73] op_sel_hi:[1,0,1]
	v_pk_fma_f32 v[74:75], v[214:215], s[8:9], v[74:75] op_sel_hi:[1,0,1]
	global_store_dwordx4 v[230:231], v[72:75], off offset:64
	v_pk_mul_f32 v[68:69], v[68:69], v[92:93]
	v_pk_add_f32 v[216:217], v[216:217], v[128:129] op_sel_hi:[1,0] neg_lo:[0,1] neg_hi:[0,1]
	v_pk_mul_f32 v[70:71], v[70:71], v[94:95]
	v_pk_add_f32 v[218:219], v[218:219], v[128:129] op_sel_hi:[1,0] neg_lo:[0,1] neg_hi:[0,1]
	v_pk_mul_f32 v[216:217], v[216:217], v[170:171] op_sel_hi:[1,0]
	v_pk_mul_f32 v[218:219], v[218:219], v[170:171] op_sel_hi:[1,0]
	v_pk_fma_f32 v[216:217], v[104:105], v[216:217], v[142:143]
	v_pk_fma_f32 v[218:219], v[106:107], v[218:219], v[144:145]
	v_pk_fma_f32 v[68:69], v[216:217], s[8:9], v[68:69] op_sel_hi:[1,0,1]
	v_pk_fma_f32 v[70:71], v[218:219], s[8:9], v[70:71] op_sel_hi:[1,0,1]
	global_store_dwordx4 v[230:231], v[68:71], off offset:128
	v_pk_mul_f32 v[64:65], v[64:65], v[244:245]
	v_pk_add_f32 v[220:221], v[220:221], v[128:129] op_sel_hi:[1,0] neg_lo:[0,1] neg_hi:[0,1]
	v_pk_mul_f32 v[66:67], v[66:67], v[246:247]
	v_pk_add_f32 v[222:223], v[222:223], v[128:129] op_sel_hi:[1,0] neg_lo:[0,1] neg_hi:[0,1]
	v_pk_mul_f32 v[220:221], v[220:221], v[170:171] op_sel_hi:[1,0]
	v_pk_mul_f32 v[222:223], v[222:223], v[170:171] op_sel_hi:[1,0]
	v_pk_fma_f32 v[220:221], v[108:109], v[220:221], v[146:147]
	v_pk_fma_f32 v[222:223], v[110:111], v[222:223], v[148:149]
	v_pk_fma_f32 v[64:65], v[220:221], s[8:9], v[64:65] op_sel_hi:[1,0,1]
	v_pk_fma_f32 v[66:67], v[222:223], s[8:9], v[66:67] op_sel_hi:[1,0,1]
	global_store_dwordx4 v[230:231], v[64:67], off offset:192
	v_add_u32_e32 v254, 32, v237
	v_add_u32_e32 v236, 0xfffff000, v254
	v_cmp_lt_i32_e32 vcc, 0xfff, v254
	v_lshrrev_b32_e32 v236, 10, v236
	v_lshlrev_b32_e32 v224, 3, v254
	v_lshlrev_b32_e32 v254, 12, v254
	v_add_u32_e32 v236, 1, v236
	v_mov_b32_e32 v225, 0
	v_cndmask_b32_e32 v236, 0, v236, vcc
	v_lshl_add_u64 v[224:225], v[224:225], 0, s[10:11]
	v_lshl_add_u64 v[228:229], v[254:255], 0, v[250:251]
	v_add_u32_e32 v236, s4, v236
	v_mad_i64_i32 v[232:233], s[0:1], v236, s33, v[252:253]
	global_load_dwordx2 v[132:133], v[224:225], off
	v_lshl_add_u64 v[224:225], v[254:255], 0, v[248:249]
	v_add_u32_e32 v254, 48, v237
	v_add_u32_e32 v236, 0xfffff000, v254
	v_cmp_lt_i32_e32 vcc, 0xfff, v254
	v_lshrrev_b32_e32 v236, 10, v236
	v_lshlrev_b32_e32 v226, 3, v254
	v_lshlrev_b32_e32 v254, 12, v254
	v_add_u32_e32 v236, 1, v236
	v_mov_b32_e32 v227, 0
	v_cndmask_b32_e32 v236, 0, v236, vcc
	v_lshl_add_u64 v[226:227], v[226:227], 0, s[10:11]
	v_lshl_add_u64 v[230:231], v[254:255], 0, v[250:251]
	v_add_u32_e32 v236, s4, v236
	v_mad_i64_i32 v[234:235], s[0:1], v236, s33, v[252:253]
	global_load_dword v128, v[226:227], off
	global_load_dword v170, v[226:227], off offset:4
	v_lshl_add_u64 v[226:227], v[254:255], 0, v[248:249]
	global_load_dwordx4 v[154:157], v[224:225], off
	global_load_dwordx4 v[116:119], v[232:233], off
	global_load_dwordx4 v[158:161], v[224:225], off offset:64
	global_load_dwordx4 v[120:123], v[232:233], off offset:64
	global_load_dwordx4 v[162:165], v[224:225], off offset:128
	global_load_dwordx4 v[124:127], v[232:233], off offset:128
	global_load_dwordx4 v[166:169], v[224:225], off offset:192
	global_load_dwordx4 v[134:137], v[232:233], off offset:192
	global_load_dwordx4 v[208:211], v[226:227], off
	global_load_dwordx4 v[138:141], v[234:235], off
	global_load_dwordx4 v[212:215], v[226:227], off offset:64
	global_load_dwordx4 v[200:203], v[234:235], off offset:64
	global_load_dwordx4 v[216:219], v[226:227], off offset:128
	global_load_dwordx4 v[92:95], v[234:235], off offset:128
	global_load_dwordx4 v[220:223], v[226:227], off offset:192
	global_load_dwordx4 v[244:247], v[234:235], off offset:192
	s_waitcnt vmcnt(0)
	v_pk_mul_f32 v[60:61], v[60:61], v[116:117]
	v_pk_add_f32 v[154:155], v[154:155], v[132:133] op_sel_hi:[1,0] neg_lo:[0,1] neg_hi:[0,1]
	v_pk_mul_f32 v[62:63], v[62:63], v[118:119]
	v_pk_add_f32 v[156:157], v[156:157], v[132:133] op_sel_hi:[1,0] neg_lo:[0,1] neg_hi:[0,1]
	v_pk_mul_f32 v[154:155], v[154:155], v[132:133] op_sel:[0,1] op_sel_hi:[1,1]
	v_pk_mul_f32 v[156:157], v[156:157], v[132:133] op_sel:[0,1] op_sel_hi:[1,1]
	v_pk_fma_f32 v[154:155], v[96:97], v[154:155], v[112:113]
	v_pk_fma_f32 v[156:157], v[98:99], v[156:157], v[114:115]
	v_pk_fma_f32 v[60:61], v[154:155], s[8:9], v[60:61] op_sel_hi:[1,0,1]
	v_pk_fma_f32 v[62:63], v[156:157], s[8:9], v[62:63] op_sel_hi:[1,0,1]
	global_store_dwordx4 v[228:229], v[60:63], off
	v_pk_mul_f32 v[56:57], v[56:57], v[120:121]
	v_pk_add_f32 v[158:159], v[158:159], v[132:133] op_sel_hi:[1,0] neg_lo:[0,1] neg_hi:[0,1]
	v_pk_mul_f32 v[58:59], v[58:59], v[122:123]
	v_pk_add_f32 v[160:161], v[160:161], v[132:133] op_sel_hi:[1,0] neg_lo:[0,1] neg_hi:[0,1]
	v_pk_mul_f32 v[158:159], v[158:159], v[132:133] op_sel:[0,1] op_sel_hi:[1,1]
	v_pk_mul_f32 v[160:161], v[160:161], v[132:133] op_sel:[0,1] op_sel_hi:[1,1]
	v_pk_fma_f32 v[158:159], v[100:101], v[158:159], v[150:151]
	v_pk_fma_f32 v[160:161], v[102:103], v[160:161], v[152:153]
	v_pk_fma_f32 v[56:57], v[158:159], s[8:9], v[56:57] op_sel_hi:[1,0,1]
	v_pk_fma_f32 v[58:59], v[160:161], s[8:9], v[58:59] op_sel_hi:[1,0,1]
	global_store_dwordx4 v[228:229], v[56:59], off offset:64
	v_pk_mul_f32 v[52:53], v[52:53], v[124:125]
	v_pk_add_f32 v[162:163], v[162:163], v[132:133] op_sel_hi:[1,0] neg_lo:[0,1] neg_hi:[0,1]
	v_pk_mul_f32 v[54:55], v[54:55], v[126:127]
	v_pk_add_f32 v[164:165], v[164:165], v[132:133] op_sel_hi:[1,0] neg_lo:[0,1] neg_hi:[0,1]
	v_pk_mul_f32 v[162:163], v[162:163], v[132:133] op_sel:[0,1] op_sel_hi:[1,1]
	v_pk_mul_f32 v[164:165], v[164:165], v[132:133] op_sel:[0,1] op_sel_hi:[1,1]
	v_pk_fma_f32 v[162:163], v[104:105], v[162:163], v[142:143]
	v_pk_fma_f32 v[164:165], v[106:107], v[164:165], v[144:145]
	v_pk_fma_f32 v[52:53], v[162:163], s[8:9], v[52:53] op_sel_hi:[1,0,1]
	v_pk_fma_f32 v[54:55], v[164:165], s[8:9], v[54:55] op_sel_hi:[1,0,1]
	global_store_dwordx4 v[228:229], v[52:55], off offset:128
	v_pk_mul_f32 v[48:49], v[48:49], v[134:135]
	v_pk_add_f32 v[166:167], v[166:167], v[132:133] op_sel_hi:[1,0] neg_lo:[0,1] neg_hi:[0,1]
	v_pk_mul_f32 v[50:51], v[50:51], v[136:137]
	v_pk_add_f32 v[168:169], v[168:169], v[132:133] op_sel_hi:[1,0] neg_lo:[0,1] neg_hi:[0,1]
	v_pk_mul_f32 v[166:167], v[166:167], v[132:133] op_sel:[0,1] op_sel_hi:[1,1]
	v_pk_mul_f32 v[168:169], v[168:169], v[132:133] op_sel:[0,1] op_sel_hi:[1,1]
	v_pk_fma_f32 v[166:167], v[108:109], v[166:167], v[146:147]
	v_pk_fma_f32 v[168:169], v[110:111], v[168:169], v[148:149]
	v_pk_fma_f32 v[48:49], v[166:167], s[8:9], v[48:49] op_sel_hi:[1,0,1]
	v_pk_fma_f32 v[50:51], v[168:169], s[8:9], v[50:51] op_sel_hi:[1,0,1]
	global_store_dwordx4 v[228:229], v[48:51], off offset:192
	v_pk_mul_f32 v[44:45], v[44:45], v[138:139]
	v_pk_add_f32 v[208:209], v[208:209], v[128:129] op_sel_hi:[1,0] neg_lo:[0,1] neg_hi:[0,1]
	v_pk_mul_f32 v[46:47], v[46:47], v[140:141]
	v_pk_add_f32 v[210:211], v[210:211], v[128:129] op_sel_hi:[1,0] neg_lo:[0,1] neg_hi:[0,1]
	v_pk_mul_f32 v[208:209], v[208:209], v[170:171] op_sel_hi:[1,0]
	v_pk_mul_f32 v[210:211], v[210:211], v[170:171] op_sel_hi:[1,0]
	v_pk_fma_f32 v[208:209], v[96:97], v[208:209], v[112:113]
	v_pk_fma_f32 v[210:211], v[98:99], v[210:211], v[114:115]
	v_pk_fma_f32 v[44:45], v[208:209], s[8:9], v[44:45] op_sel_hi:[1,0,1]
	v_pk_fma_f32 v[46:47], v[210:211], s[8:9], v[46:47] op_sel_hi:[1,0,1]
	global_store_dwordx4 v[230:231], v[44:47], off
	v_pk_mul_f32 v[40:41], v[40:41], v[200:201]
	v_pk_add_f32 v[212:213], v[212:213], v[128:129] op_sel_hi:[1,0] neg_lo:[0,1] neg_hi:[0,1]
	v_pk_mul_f32 v[42:43], v[42:43], v[202:203]
	v_pk_add_f32 v[214:215], v[214:215], v[128:129] op_sel_hi:[1,0] neg_lo:[0,1] neg_hi:[0,1]
	v_pk_mul_f32 v[212:213], v[212:213], v[170:171] op_sel_hi:[1,0]
	v_pk_mul_f32 v[214:215], v[214:215], v[170:171] op_sel_hi:[1,0]
	v_pk_fma_f32 v[212:213], v[100:101], v[212:213], v[150:151]
	v_pk_fma_f32 v[214:215], v[102:103], v[214:215], v[152:153]
	v_pk_fma_f32 v[40:41], v[212:213], s[8:9], v[40:41] op_sel_hi:[1,0,1]
	v_pk_fma_f32 v[42:43], v[214:215], s[8:9], v[42:43] op_sel_hi:[1,0,1]
	global_store_dwordx4 v[230:231], v[40:43], off offset:64
	v_pk_mul_f32 v[36:37], v[36:37], v[92:93]
	v_pk_add_f32 v[216:217], v[216:217], v[128:129] op_sel_hi:[1,0] neg_lo:[0,1] neg_hi:[0,1]
	v_pk_mul_f32 v[38:39], v[38:39], v[94:95]
	v_pk_add_f32 v[218:219], v[218:219], v[128:129] op_sel_hi:[1,0] neg_lo:[0,1] neg_hi:[0,1]
	v_pk_mul_f32 v[216:217], v[216:217], v[170:171] op_sel_hi:[1,0]
	v_pk_mul_f32 v[218:219], v[218:219], v[170:171] op_sel_hi:[1,0]
	v_pk_fma_f32 v[216:217], v[104:105], v[216:217], v[142:143]
	v_pk_fma_f32 v[218:219], v[106:107], v[218:219], v[144:145]
	v_pk_fma_f32 v[36:37], v[216:217], s[8:9], v[36:37] op_sel_hi:[1,0,1]
	v_pk_fma_f32 v[38:39], v[218:219], s[8:9], v[38:39] op_sel_hi:[1,0,1]
	global_store_dwordx4 v[230:231], v[36:39], off offset:128
	v_pk_mul_f32 v[32:33], v[32:33], v[244:245]
	v_pk_add_f32 v[220:221], v[220:221], v[128:129] op_sel_hi:[1,0] neg_lo:[0,1] neg_hi:[0,1]
	v_pk_mul_f32 v[34:35], v[34:35], v[246:247]
	v_pk_add_f32 v[222:223], v[222:223], v[128:129] op_sel_hi:[1,0] neg_lo:[0,1] neg_hi:[0,1]
	v_pk_mul_f32 v[220:221], v[220:221], v[170:171] op_sel_hi:[1,0]
	v_pk_mul_f32 v[222:223], v[222:223], v[170:171] op_sel_hi:[1,0]
	v_pk_fma_f32 v[220:221], v[108:109], v[220:221], v[146:147]
	v_pk_fma_f32 v[222:223], v[110:111], v[222:223], v[148:149]
	v_pk_fma_f32 v[32:33], v[220:221], s[8:9], v[32:33] op_sel_hi:[1,0,1]
	v_pk_fma_f32 v[34:35], v[222:223], s[8:9], v[34:35] op_sel_hi:[1,0,1]
	global_store_dwordx4 v[230:231], v[32:35], off offset:192
	v_add_u32_e32 v254, 64, v237
	v_add_u32_e32 v236, 0xfffff000, v254
	v_cmp_lt_i32_e32 vcc, 0xfff, v254
	v_lshrrev_b32_e32 v236, 10, v236
	v_lshlrev_b32_e32 v224, 3, v254
	v_lshlrev_b32_e32 v254, 12, v254
	v_add_u32_e32 v236, 1, v236
	v_mov_b32_e32 v225, 0
	v_cndmask_b32_e32 v236, 0, v236, vcc
	v_lshl_add_u64 v[224:225], v[224:225], 0, s[10:11]
	v_lshl_add_u64 v[228:229], v[254:255], 0, v[250:251]
	v_add_u32_e32 v236, s4, v236
	v_mad_i64_i32 v[232:233], s[0:1], v236, s33, v[252:253]
	global_load_dwordx2 v[132:133], v[224:225], off
	v_lshl_add_u64 v[224:225], v[254:255], 0, v[248:249]
	v_add_u32_e32 v254, 80, v237
	v_add_u32_e32 v236, 0xfffff000, v254
	v_cmp_lt_i32_e32 vcc, 0xfff, v254
	v_lshrrev_b32_e32 v236, 10, v236
	v_lshlrev_b32_e32 v226, 3, v254
	v_lshlrev_b32_e32 v254, 12, v254
	v_add_u32_e32 v236, 1, v236
	v_mov_b32_e32 v227, 0
	v_cndmask_b32_e32 v236, 0, v236, vcc
	v_lshl_add_u64 v[226:227], v[226:227], 0, s[10:11]
	v_lshl_add_u64 v[230:231], v[254:255], 0, v[250:251]
	v_add_u32_e32 v236, s4, v236
	v_mad_i64_i32 v[234:235], s[0:1], v236, s33, v[252:253]
	global_load_dword v128, v[226:227], off
	global_load_dword v170, v[226:227], off offset:4
	v_lshl_add_u64 v[226:227], v[254:255], 0, v[248:249]
	global_load_dwordx4 v[154:157], v[224:225], off
	global_load_dwordx4 v[116:119], v[232:233], off
	global_load_dwordx4 v[158:161], v[224:225], off offset:64
	global_load_dwordx4 v[120:123], v[232:233], off offset:64
	global_load_dwordx4 v[162:165], v[224:225], off offset:128
	global_load_dwordx4 v[124:127], v[232:233], off offset:128
	global_load_dwordx4 v[166:169], v[224:225], off offset:192
	global_load_dwordx4 v[134:137], v[232:233], off offset:192
	global_load_dwordx4 v[208:211], v[226:227], off
	global_load_dwordx4 v[138:141], v[234:235], off
	global_load_dwordx4 v[212:215], v[226:227], off offset:64
	global_load_dwordx4 v[200:203], v[234:235], off offset:64
	global_load_dwordx4 v[216:219], v[226:227], off offset:128
	global_load_dwordx4 v[92:95], v[234:235], off offset:128
	global_load_dwordx4 v[220:223], v[226:227], off offset:192
	global_load_dwordx4 v[244:247], v[234:235], off offset:192
	s_waitcnt vmcnt(0)
	v_pk_mul_f32 v[28:29], v[28:29], v[116:117]
	v_pk_add_f32 v[154:155], v[154:155], v[132:133] op_sel_hi:[1,0] neg_lo:[0,1] neg_hi:[0,1]
	v_pk_mul_f32 v[30:31], v[30:31], v[118:119]
	v_pk_add_f32 v[156:157], v[156:157], v[132:133] op_sel_hi:[1,0] neg_lo:[0,1] neg_hi:[0,1]
	v_pk_mul_f32 v[154:155], v[154:155], v[132:133] op_sel:[0,1] op_sel_hi:[1,1]
	v_pk_mul_f32 v[156:157], v[156:157], v[132:133] op_sel:[0,1] op_sel_hi:[1,1]
	v_pk_fma_f32 v[154:155], v[96:97], v[154:155], v[112:113]
	v_pk_fma_f32 v[156:157], v[98:99], v[156:157], v[114:115]
	v_pk_fma_f32 v[28:29], v[154:155], s[8:9], v[28:29] op_sel_hi:[1,0,1]
	v_pk_fma_f32 v[30:31], v[156:157], s[8:9], v[30:31] op_sel_hi:[1,0,1]
	global_store_dwordx4 v[228:229], v[28:31], off
	v_pk_mul_f32 v[24:25], v[24:25], v[120:121]
	v_pk_add_f32 v[158:159], v[158:159], v[132:133] op_sel_hi:[1,0] neg_lo:[0,1] neg_hi:[0,1]
	v_pk_mul_f32 v[26:27], v[26:27], v[122:123]
	v_pk_add_f32 v[160:161], v[160:161], v[132:133] op_sel_hi:[1,0] neg_lo:[0,1] neg_hi:[0,1]
	v_pk_mul_f32 v[158:159], v[158:159], v[132:133] op_sel:[0,1] op_sel_hi:[1,1]
	v_pk_mul_f32 v[160:161], v[160:161], v[132:133] op_sel:[0,1] op_sel_hi:[1,1]
	v_pk_fma_f32 v[158:159], v[100:101], v[158:159], v[150:151]
	v_pk_fma_f32 v[160:161], v[102:103], v[160:161], v[152:153]
	v_pk_fma_f32 v[24:25], v[158:159], s[8:9], v[24:25] op_sel_hi:[1,0,1]
	v_pk_fma_f32 v[26:27], v[160:161], s[8:9], v[26:27] op_sel_hi:[1,0,1]
	global_store_dwordx4 v[228:229], v[24:27], off offset:64
	v_pk_mul_f32 v[20:21], v[20:21], v[124:125]
	v_pk_add_f32 v[162:163], v[162:163], v[132:133] op_sel_hi:[1,0] neg_lo:[0,1] neg_hi:[0,1]
	v_pk_mul_f32 v[22:23], v[22:23], v[126:127]
	v_pk_add_f32 v[164:165], v[164:165], v[132:133] op_sel_hi:[1,0] neg_lo:[0,1] neg_hi:[0,1]
	v_pk_mul_f32 v[162:163], v[162:163], v[132:133] op_sel:[0,1] op_sel_hi:[1,1]
	v_pk_mul_f32 v[164:165], v[164:165], v[132:133] op_sel:[0,1] op_sel_hi:[1,1]
	v_pk_fma_f32 v[162:163], v[104:105], v[162:163], v[142:143]
	v_pk_fma_f32 v[164:165], v[106:107], v[164:165], v[144:145]
	v_pk_fma_f32 v[20:21], v[162:163], s[8:9], v[20:21] op_sel_hi:[1,0,1]
	v_pk_fma_f32 v[22:23], v[164:165], s[8:9], v[22:23] op_sel_hi:[1,0,1]
	global_store_dwordx4 v[228:229], v[20:23], off offset:128
	v_pk_mul_f32 v[16:17], v[16:17], v[134:135]
	v_pk_add_f32 v[166:167], v[166:167], v[132:133] op_sel_hi:[1,0] neg_lo:[0,1] neg_hi:[0,1]
	v_pk_mul_f32 v[18:19], v[18:19], v[136:137]
	v_pk_add_f32 v[168:169], v[168:169], v[132:133] op_sel_hi:[1,0] neg_lo:[0,1] neg_hi:[0,1]
	v_pk_mul_f32 v[166:167], v[166:167], v[132:133] op_sel:[0,1] op_sel_hi:[1,1]
	v_pk_mul_f32 v[168:169], v[168:169], v[132:133] op_sel:[0,1] op_sel_hi:[1,1]
	v_pk_fma_f32 v[166:167], v[108:109], v[166:167], v[146:147]
	v_pk_fma_f32 v[168:169], v[110:111], v[168:169], v[148:149]
	v_pk_fma_f32 v[16:17], v[166:167], s[8:9], v[16:17] op_sel_hi:[1,0,1]
	v_pk_fma_f32 v[18:19], v[168:169], s[8:9], v[18:19] op_sel_hi:[1,0,1]
	global_store_dwordx4 v[228:229], v[16:19], off offset:192
	v_pk_mul_f32 v[12:13], v[12:13], v[138:139]
	v_pk_add_f32 v[208:209], v[208:209], v[128:129] op_sel_hi:[1,0] neg_lo:[0,1] neg_hi:[0,1]
	v_pk_mul_f32 v[14:15], v[14:15], v[140:141]
	v_pk_add_f32 v[210:211], v[210:211], v[128:129] op_sel_hi:[1,0] neg_lo:[0,1] neg_hi:[0,1]
	v_pk_mul_f32 v[208:209], v[208:209], v[170:171] op_sel_hi:[1,0]
	v_pk_mul_f32 v[210:211], v[210:211], v[170:171] op_sel_hi:[1,0]
	v_pk_fma_f32 v[208:209], v[96:97], v[208:209], v[112:113]
	v_pk_fma_f32 v[210:211], v[98:99], v[210:211], v[114:115]
	v_pk_fma_f32 v[12:13], v[208:209], s[8:9], v[12:13] op_sel_hi:[1,0,1]
	v_pk_fma_f32 v[14:15], v[210:211], s[8:9], v[14:15] op_sel_hi:[1,0,1]
	global_store_dwordx4 v[230:231], v[12:15], off
	v_pk_mul_f32 v[8:9], v[8:9], v[200:201]
	v_pk_add_f32 v[212:213], v[212:213], v[128:129] op_sel_hi:[1,0] neg_lo:[0,1] neg_hi:[0,1]
	v_pk_mul_f32 v[10:11], v[10:11], v[202:203]
	v_pk_add_f32 v[214:215], v[214:215], v[128:129] op_sel_hi:[1,0] neg_lo:[0,1] neg_hi:[0,1]
	v_pk_mul_f32 v[212:213], v[212:213], v[170:171] op_sel_hi:[1,0]
	v_pk_mul_f32 v[214:215], v[214:215], v[170:171] op_sel_hi:[1,0]
	v_pk_fma_f32 v[212:213], v[100:101], v[212:213], v[150:151]
	v_pk_fma_f32 v[214:215], v[102:103], v[214:215], v[152:153]
	v_pk_fma_f32 v[8:9], v[212:213], s[8:9], v[8:9] op_sel_hi:[1,0,1]
	v_pk_fma_f32 v[10:11], v[214:215], s[8:9], v[10:11] op_sel_hi:[1,0,1]
	global_store_dwordx4 v[230:231], v[8:11], off offset:64
	v_pk_mul_f32 v[4:5], v[4:5], v[92:93]
	v_pk_add_f32 v[216:217], v[216:217], v[128:129] op_sel_hi:[1,0] neg_lo:[0,1] neg_hi:[0,1]
	v_pk_mul_f32 v[6:7], v[6:7], v[94:95]
	v_pk_add_f32 v[218:219], v[218:219], v[128:129] op_sel_hi:[1,0] neg_lo:[0,1] neg_hi:[0,1]
	v_pk_mul_f32 v[216:217], v[216:217], v[170:171] op_sel_hi:[1,0]
	v_pk_mul_f32 v[218:219], v[218:219], v[170:171] op_sel_hi:[1,0]
	v_pk_fma_f32 v[216:217], v[104:105], v[216:217], v[142:143]
	v_pk_fma_f32 v[218:219], v[106:107], v[218:219], v[144:145]
	v_pk_fma_f32 v[4:5], v[216:217], s[8:9], v[4:5] op_sel_hi:[1,0,1]
	v_pk_fma_f32 v[6:7], v[218:219], s[8:9], v[6:7] op_sel_hi:[1,0,1]
	global_store_dwordx4 v[230:231], v[4:7], off offset:128
	v_pk_mul_f32 v[0:1], v[0:1], v[244:245]
	v_pk_add_f32 v[220:221], v[220:221], v[128:129] op_sel_hi:[1,0] neg_lo:[0,1] neg_hi:[0,1]
	v_pk_mul_f32 v[2:3], v[2:3], v[246:247]
	v_pk_add_f32 v[222:223], v[222:223], v[128:129] op_sel_hi:[1,0] neg_lo:[0,1] neg_hi:[0,1]
	v_pk_mul_f32 v[220:221], v[220:221], v[170:171] op_sel_hi:[1,0]
	v_pk_mul_f32 v[222:223], v[222:223], v[170:171] op_sel_hi:[1,0]
	v_pk_fma_f32 v[220:221], v[108:109], v[220:221], v[146:147]
	v_pk_fma_f32 v[222:223], v[110:111], v[222:223], v[148:149]
	v_pk_fma_f32 v[0:1], v[220:221], s[8:9], v[0:1] op_sel_hi:[1,0,1]
	v_pk_fma_f32 v[2:3], v[222:223], s[8:9], v[2:3] op_sel_hi:[1,0,1]
	global_store_dwordx4 v[230:231], v[0:3], off offset:192
	v_readlane_b32 s9, v242, 26
	v_readlane_b32 s10, v242, 27
	v_readlane_b32 s11, v242, 28
	v_readlane_b32 s12, v242, 29
	v_readlane_b32 s13, v242, 30
	v_readlane_b32 s14, v242, 31
	v_readlane_b32 s15, v242, 32
	v_readlane_b32 s16, v242, 33
	v_readlane_b32 s17, v242, 34
	v_readlane_b32 s18, v242, 35
	v_readlane_b32 s19, v242, 36
	v_readlane_b32 s20, v242, 37
	v_readlane_b32 s21, v242, 38
	v_readlane_b32 s22, v242, 39
	v_readlane_b32 s23, v242, 40
	s_mov_b64 s[24:25], 0x5000
	s_movk_i32 s6, 0xfff
	s_waitcnt lgkmcnt(0)
	s_barrier
	s_cmpk_gt_i32 s5, 0xff
	s_cbranch_scc0 .LBB0_52

.LBB0_128:
	s_mul_i32 s5, s10, 0x5000
	v_add_u32_e32 v156, s5, v142
	v_lshl_add_u64 v[126:127], v[124:125], 0, s[6:7]
	v_readfirstlane_b32 s5, v156
	v_add_u32_e32 v136, 0x1000, v156
	v_lshl_add_u64 v[134:135], v[126:127], 0, s[2:3]
	s_mov_b32 m0, s5
	v_lshl_add_u64 v[138:139], v[122:123], 0, s[6:7]
	v_readfirstlane_b32 s5, v136
	s_waitcnt vmcnt(5)
	s_barrier
	global_load_lds_dwordx4 v[134:135], off
	v_lshl_add_u64 v[134:135], v[138:139], 0, s[2:3]
	s_mov_b32 m0, s5
	v_add_u32_e32 v140, 0x2000, v156
	global_load_lds_dwordx4 v[134:135], off
	v_lshl_add_u64 v[134:135], v[120:121], 0, s[6:7]
	v_readfirstlane_b32 s5, v140
	v_lshl_add_u64 v[136:137], v[134:135], 0, s[2:3]
	s_mov_b32 m0, s5
	v_add_u32_e32 v154, 0x3000, v156
	global_load_lds_dwordx4 v[136:137], off
	v_lshl_add_u64 v[136:137], v[118:119], 0, s[6:7]
	v_readfirstlane_b32 s5, v154
	v_lshl_add_u64 v[140:141], v[136:137], 0, s[2:3]
	s_mov_b32 m0, s5
	v_add_u32_e32 v156, 0x4000, v156
	global_load_lds_dwordx4 v[140:141], off
	v_lshl_add_u64 v[140:141], v[116:117], 0, s[6:7]
	v_readfirstlane_b32 s5, v156
	v_lshl_add_u64 v[154:155], v[140:141], 0, s[2:3]
	s_mov_b32 m0, s5
	s_mul_i32 s5, s1, 0x5000
	global_load_lds_dwordx4 v[154:155], off
	v_or_b32_e32 v154, s5, v147
	v_add_u32_e32 v170, v154, v128
	ds_read_b128 v[154:157], v170
	ds_read_b128 v[158:161], v170 offset:1024
	ds_read_b128 v[162:165], v170 offset:2048
	ds_read_b128 v[166:169], v170 offset:3072
	ds_read_b128 v[200:203], v170 offset:4096
	ds_read_b128 v[204:207], v170 offset:5120
	v_or_b32_e32 v170, s5, v149
	v_add_u32_e32 v170, v170, v148
	s_add_i32 s1, s1, 1
	s_add_i32 s10, s10, 1
	ds_read_b128 v[208:211], v170 offset:12288
	ds_read_b128 v[212:215], v170 offset:13312
	ds_read_b128 v[216:219], v170 offset:14336
	ds_read_b128 v[220:223], v170 offset:15360
	s_cmp_lg_u32 s1, 3
	s_cselect_b32 s1, s1, 0
	s_cmp_lg_u32 s10, 3
	s_cselect_b32 s5, s10, 0
	s_mul_i32 s10, s5, 0x5000
	s_waitcnt lgkmcnt(0)
	v_mfma_f32_16x16x32_bf16 v[92:95], v[208:211], v[154:157], v[92:95]
	v_lshl_add_u64 v[126:127], v[126:127], 0, s[30:31]
	s_waitcnt vmcnt(5)
	s_barrier
	v_mfma_f32_16x16x32_bf16 v[88:91], v[212:215], v[154:157], v[88:91]
	s_add_i32 s5, s5, 1
	v_mfma_f32_16x16x32_bf16 v[84:87], v[216:219], v[154:157], v[84:87]
	v_mfma_f32_16x16x32_bf16 v[80:83], v[220:223], v[154:157], v[80:83]
	v_add_u32_e32 v154, s10, v142
	s_nop 0
	v_readfirstlane_b32 s10, v154
	s_mov_b32 m0, s10
	v_mfma_f32_16x16x32_bf16 v[76:79], v[208:211], v[158:161], v[76:79]
	global_load_lds_dwordx4 v[126:127], off
	v_lshl_add_u64 v[126:127], v[138:139], 0, s[30:31]
	v_add_u32_e32 v138, 0x1000, v154
	v_mfma_f32_16x16x32_bf16 v[72:75], v[212:215], v[158:161], v[72:75]
	v_readfirstlane_b32 s10, v138
	s_mov_b32 m0, s10
	s_nop 0
	global_load_lds_dwordx4 v[126:127], off
	v_lshl_add_u64 v[126:127], v[134:135], 0, s[30:31]
	v_add_u32_e32 v134, 0x2000, v154
	v_mfma_f32_16x16x32_bf16 v[68:71], v[216:219], v[158:161], v[68:71]
	v_readfirstlane_b32 s10, v134
	v_add_u32_e32 v134, 0x3000, v154
	s_mov_b32 m0, s10
	v_readfirstlane_b32 s10, v134
	v_add_u32_e32 v134, 0x4000, v154
	global_load_lds_dwordx4 v[126:127], off
	v_lshl_add_u64 v[126:127], v[136:137], 0, s[30:31]
	s_mov_b32 m0, s10
	v_readfirstlane_b32 s10, v134
	global_load_lds_dwordx4 v[126:127], off
	v_lshl_add_u64 v[126:127], v[140:141], 0, s[30:31]
	s_mov_b32 m0, s10
	s_mul_i32 s10, s1, 0x5000
	global_load_lds_dwordx4 v[126:127], off
	v_or_b32_e32 v126, s10, v147
	v_add_u32_e32 v126, v126, v128
	v_mfma_f32_16x16x32_bf16 v[64:67], v[220:223], v[158:161], v[64:67]
	s_add_i32 s1, s1, 1
	s_cmp_lg_u32 s1, 3
	s_cselect_b32 s1, s1, 0
	v_mfma_f32_16x16x32_bf16 v[60:63], v[208:211], v[162:165], v[60:63]
	s_cmp_lg_u32 s5, 3
	v_mfma_f32_16x16x32_bf16 v[56:59], v[212:215], v[162:165], v[56:59]
	v_mfma_f32_16x16x32_bf16 v[52:55], v[216:219], v[162:165], v[52:55]
	v_mfma_f32_16x16x32_bf16 v[48:51], v[220:223], v[162:165], v[48:51]
	v_mfma_f32_16x16x32_bf16 v[44:47], v[208:211], v[166:169], v[44:47]
	v_mfma_f32_16x16x32_bf16 v[40:43], v[212:215], v[166:169], v[40:43]
	v_mfma_f32_16x16x32_bf16 v[36:39], v[216:219], v[166:169], v[36:39]
	v_mfma_f32_16x16x32_bf16 v[32:35], v[220:223], v[166:169], v[32:35]
	ds_read_b128 v[134:137], v126
	ds_read_b128 v[138:141], v126 offset:1024
	ds_read_b128 v[154:157], v126 offset:2048
	ds_read_b128 v[158:161], v126 offset:3072
	ds_read_b128 v[162:165], v126 offset:4096
	ds_read_b128 v[166:169], v126 offset:5120
	v_or_b32_e32 v126, s10, v149
	v_add_u32_e32 v126, v126, v148
	v_mfma_f32_16x16x32_bf16 v[28:31], v[208:211], v[200:203], v[28:31]
	s_cselect_b32 s10, s5, 0
	s_add_u32 s6, s6, 0x80
	s_addc_u32 s7, s7, 0
	v_mfma_f32_16x16x32_bf16 v[24:27], v[212:215], v[200:203], v[24:27]
	s_cmpk_eq_i32 s6, 0x780
	v_mfma_f32_16x16x32_bf16 v[20:23], v[216:219], v[200:203], v[20:23]
	v_mfma_f32_16x16x32_bf16 v[16:19], v[220:223], v[200:203], v[16:19]
	v_mfma_f32_16x16x32_bf16 v[8:11], v[208:211], v[204:207], v[8:11]
	v_mfma_f32_16x16x32_bf16 v[4:7], v[212:215], v[204:207], v[4:7]
	v_mfma_f32_16x16x32_bf16 v[12:15], v[216:219], v[204:207], v[12:15]
	v_mfma_f32_16x16x32_bf16 v[0:3], v[220:223], v[204:207], v[0:3]
	ds_read_b128 v[200:203], v126 offset:12288
	ds_read_b128 v[204:207], v126 offset:13312
	ds_read_b128 v[208:211], v126 offset:14336
	ds_read_b128 v[212:215], v126 offset:15360
	s_waitcnt lgkmcnt(0)
	v_mfma_f32_16x16x32_bf16 v[92:95], v[200:203], v[134:137], v[92:95]
	v_mfma_f32_16x16x32_bf16 v[88:91], v[204:207], v[134:137], v[88:91]
	v_mfma_f32_16x16x32_bf16 v[84:87], v[208:211], v[134:137], v[84:87]
	v_mfma_f32_16x16x32_bf16 v[80:83], v[212:215], v[134:137], v[80:83]
	v_mfma_f32_16x16x32_bf16 v[76:79], v[200:203], v[138:141], v[76:79]
	v_mfma_f32_16x16x32_bf16 v[72:75], v[204:207], v[138:141], v[72:75]
	v_mfma_f32_16x16x32_bf16 v[68:71], v[208:211], v[138:141], v[68:71]
	v_mfma_f32_16x16x32_bf16 v[64:67], v[212:215], v[138:141], v[64:67]
	v_mfma_f32_16x16x32_bf16 v[60:63], v[200:203], v[154:157], v[60:63]
	v_mfma_f32_16x16x32_bf16 v[56:59], v[204:207], v[154:157], v[56:59]
	v_mfma_f32_16x16x32_bf16 v[52:55], v[208:211], v[154:157], v[52:55]
	v_mfma_f32_16x16x32_bf16 v[48:51], v[212:215], v[154:157], v[48:51]
	v_mfma_f32_16x16x32_bf16 v[44:47], v[200:203], v[158:161], v[44:47]
	v_mfma_f32_16x16x32_bf16 v[40:43], v[204:207], v[158:161], v[40:43]
	v_mfma_f32_16x16x32_bf16 v[36:39], v[208:211], v[158:161], v[36:39]
	v_mfma_f32_16x16x32_bf16 v[32:35], v[212:215], v[158:161], v[32:35]
	v_mfma_f32_16x16x32_bf16 v[28:31], v[200:203], v[162:165], v[28:31]
	v_mfma_f32_16x16x32_bf16 v[24:27], v[204:207], v[162:165], v[24:27]
	v_mfma_f32_16x16x32_bf16 v[20:23], v[208:211], v[162:165], v[20:23]
	v_mfma_f32_16x16x32_bf16 v[16:19], v[212:215], v[162:165], v[16:19]
	v_mfma_f32_16x16x32_bf16 v[8:11], v[200:203], v[166:169], v[8:11]
	v_mfma_f32_16x16x32_bf16 v[4:7], v[204:207], v[166:169], v[4:7]
	v_mfma_f32_16x16x32_bf16 v[12:15], v[208:211], v[166:169], v[12:15]
	v_mfma_f32_16x16x32_bf16 v[0:3], v[212:215], v[166:169], v[0:3]
	s_cbranch_scc0 .LBB0_128
	v_add_u32_e32 v170, v147, v128
	v_add_u32_e32 v172, v149, v148
	s_waitcnt vmcnt(5)
	s_barrier
	ds_read_b128 v[116:119], v170
	ds_read_b128 v[120:123], v170 offset:1024
	ds_read_b128 v[124:127], v170 offset:2048
	ds_read_b128 v[134:137], v170 offset:3072
	ds_read_b128 v[138:141], v170 offset:4096
	ds_read_b128 v[154:157], v170 offset:5120
	ds_read_b128 v[158:161], v172 offset:12288
	ds_read_b128 v[162:165], v172 offset:13312
	ds_read_b128 v[166:169], v172 offset:14336
	ds_read_b128 v[200:203], v172 offset:15360
	s_waitcnt lgkmcnt(0)
	v_mfma_f32_16x16x32_bf16 v[92:95], v[158:161], v[116:119], v[92:95]
	s_waitcnt vmcnt(0)
	s_barrier
	v_readlane_b32 s12, v243, 5
	v_mfma_f32_16x16x32_bf16 v[88:91], v[162:165], v[116:119], v[88:91]
	v_readlane_b32 s18, v243, 11
	v_readlane_b32 s19, v243, 12
	v_readlane_b32 s13, v243, 6
	v_mfma_f32_16x16x32_bf16 v[84:87], v[166:169], v[116:119], v[84:87]
	v_readlane_b32 s14, v243, 7
	v_readlane_b32 s15, v243, 8
	v_readlane_b32 s16, v243, 9
	v_mfma_f32_16x16x32_bf16 v[80:83], v[200:203], v[116:119], v[80:83]
	v_readlane_b32 s17, v243, 10
	v_readlane_b32 s20, v243, 13
	v_readlane_b32 s21, v243, 14
	v_mfma_f32_16x16x32_bf16 v[76:79], v[158:161], v[120:123], v[76:79]
	v_readlane_b32 s22, v243, 15
	v_readlane_b32 s23, v243, 16
	v_readlane_b32 s24, v243, 17
	v_mfma_f32_16x16x32_bf16 v[72:75], v[162:165], v[120:123], v[72:75]
	v_readlane_b32 s25, v243, 18
	v_readlane_b32 s26, v243, 19
	v_readlane_b32 s27, v243, 20
	v_mfma_f32_16x16x32_bf16 v[68:71], v[166:169], v[120:123], v[68:71]
	s_mov_b64 s[10:11], 0x2000
	s_mov_b32 s6, 0x3fd744fd
	s_add_i32 s9, s9, s51
	v_mfma_f32_16x16x32_bf16 v[64:67], v[200:203], v[120:123], v[64:67]
	s_cmpk_gt_i32 s9, 0xff
	v_mfma_f32_16x16x32_bf16 v[60:63], v[158:161], v[124:127], v[60:63]
	v_mfma_f32_16x16x32_bf16 v[56:59], v[162:165], v[124:127], v[56:59]
	v_mfma_f32_16x16x32_bf16 v[52:55], v[166:169], v[124:127], v[52:55]
	v_mfma_f32_16x16x32_bf16 v[48:51], v[200:203], v[124:127], v[48:51]
	v_mfma_f32_16x16x32_bf16 v[44:47], v[158:161], v[134:137], v[44:47]
	v_mfma_f32_16x16x32_bf16 v[40:43], v[162:165], v[134:137], v[40:43]
	v_mfma_f32_16x16x32_bf16 v[36:39], v[166:169], v[134:137], v[36:39]
	v_mfma_f32_16x16x32_bf16 v[32:35], v[200:203], v[134:137], v[32:35]
	v_mfma_f32_16x16x32_bf16 v[28:31], v[158:161], v[138:141], v[28:31]
	v_mfma_f32_16x16x32_bf16 v[24:27], v[162:165], v[138:141], v[24:27]
	v_mfma_f32_16x16x32_bf16 v[20:23], v[166:169], v[138:141], v[20:23]
	v_mfma_f32_16x16x32_bf16 v[16:19], v[200:203], v[138:141], v[16:19]
	v_mfma_f32_16x16x32_bf16 v[8:11], v[158:161], v[154:157], v[8:11]
	v_mfma_f32_16x16x32_bf16 v[4:7], v[162:165], v[154:157], v[4:7]
	v_mfma_f32_16x16x32_bf16 v[116:119], v[166:169], v[154:157], v[12:15]
	v_mfma_f32_16x16x32_bf16 v[0:3], v[200:203], v[154:157], v[0:3]
	s_nop 1
	ds_read_b128 v[12:15], v170 offset:20480
	ds_read_b128 v[120:123], v170 offset:21504
	ds_read_b128 v[124:127], v170 offset:22528
	ds_read_b128 v[134:137], v170 offset:23552
	ds_read_b128 v[138:141], v170 offset:24576
	ds_read_b128 v[154:157], v170 offset:25600
	ds_read_b128 v[158:161], v172 offset:32768
	ds_read_b128 v[162:165], v172 offset:33792
	ds_read_b128 v[166:169], v172 offset:34816
	ds_read_b128 v[200:203], v172 offset:35840
	s_waitcnt lgkmcnt(0)
	v_mfma_f32_16x16x32_bf16 v[76:79], v[158:161], v[120:123], v[76:79]
	v_mfma_f32_16x16x32_bf16 v[72:75], v[162:165], v[120:123], v[72:75]
	v_mfma_f32_16x16x32_bf16 v[68:71], v[166:169], v[120:123], v[68:71]
	v_mfma_f32_16x16x32_bf16 v[64:67], v[200:203], v[120:123], v[64:67]
	v_mfma_f32_16x16x32_bf16 v[204:207], v[158:161], v[12:15], v[92:95]
	v_mfma_f32_16x16x32_bf16 v[88:91], v[162:165], v[12:15], v[88:91]
	v_mfma_f32_16x16x32_bf16 v[84:87], v[166:169], v[12:15], v[84:87]
	v_mfma_f32_16x16x32_bf16 v[80:83], v[200:203], v[12:15], v[80:83]
	v_mfma_f32_16x16x32_bf16 v[12:15], v[158:161], v[154:157], v[8:11]
	v_mfma_f32_16x16x32_bf16 v[8:11], v[162:165], v[154:157], v[4:7]
	v_mfma_f32_16x16x32_bf16 v[4:7], v[166:169], v[154:157], v[116:119]
	v_mfma_f32_16x16x32_bf16 v[28:31], v[158:161], v[138:141], v[28:31]
	v_mfma_f32_16x16x32_bf16 v[24:27], v[162:165], v[138:141], v[24:27]
	v_mfma_f32_16x16x32_bf16 v[20:23], v[166:169], v[138:141], v[20:23]
	v_mfma_f32_16x16x32_bf16 v[16:19], v[200:203], v[138:141], v[16:19]
	v_mfma_f32_16x16x32_bf16 v[60:63], v[158:161], v[124:127], v[60:63]
	v_mfma_f32_16x16x32_bf16 v[56:59], v[162:165], v[124:127], v[56:59]
	v_mfma_f32_16x16x32_bf16 v[52:55], v[166:169], v[124:127], v[52:55]
	v_mfma_f32_16x16x32_bf16 v[48:51], v[200:203], v[124:127], v[48:51]
	v_mfma_f32_16x16x32_bf16 v[44:47], v[158:161], v[134:137], v[44:47]
	v_mfma_f32_16x16x32_bf16 v[40:43], v[162:165], v[134:137], v[40:43]
	v_mfma_f32_16x16x32_bf16 v[36:39], v[166:169], v[134:137], v[36:39]
	v_mfma_f32_16x16x32_bf16 v[32:35], v[200:203], v[134:137], v[32:35]
	v_mfma_f32_16x16x32_bf16 v[0:3], v[200:203], v[154:157], v[0:3]
	v_readlane_b32 s10, v241, 9
	s_cmp_eq_u32 s10, 7
	s_cbranch_scc0 .Lout_epi_ln
	v_readlane_b32 s10, v242, 25
	v_readlane_b32 s11, v242, 26
	v_readlane_b32 s12, v242, 29
	v_readlane_b32 s13, v242, 30
	v_readlane_b32 s14, v243, 11
	v_readlane_b32 s15, v243, 12
	s_mov_b32 s6, 0x3fd744fd
	v_add_u32_e32 v236, s0, v145
	v_or_b32_e32 v254, s4, v146
	v_mov_b32_e32 v255, 0
	v_or_b32_e32 v237, v236, v133
	v_lshlrev_b64 v[254:255], 2, v[254:255]
	s_nop 0
	v_lshl_add_u64 v[248:249], s[10:11], 0, v[254:255]
	v_lshl_add_u64 v[250:251], s[12:13], 0, v[254:255]
	v_lshl_add_u64 v[252:253], s[14:15], 0, v[254:255]
	s_mov_b64 s[10:11], 0x2000
	v_mov_b32_e32 v255, 0
	v_lshl_add_u64 v[252:253], v[252:253], 0, s[10:11]
	v_add_u32_e32 v254, 0, v237
	v_add_u32_e32 v236, 0xfffff000, v254
	v_cmp_lt_i32_e32 vcc, 0xfff, v254
	v_lshrrev_b32_e32 v236, 10, v236
	v_lshlrev_b32_e32 v254, 12, v254
	v_add_u32_e32 v236, 1, v236
	v_cndmask_b32_e32 v236, 0, v236, vcc
	v_lshl_add_u64 v[224:225], v[254:255], 0, v[248:249]
	v_lshl_add_u64 v[228:229], v[254:255], 0, v[250:251]
	v_add_u32_e32 v236, s8, v236
	v_mad_i64_i32 v[232:233], s[0:1], v236, s33, v[252:253]
	v_add_u32_e32 v254, 16, v237
	v_add_u32_e32 v236, 0xfffff000, v254
	v_cmp_lt_i32_e32 vcc, 0xfff, v254
	v_lshrrev_b32_e32 v236, 10, v236
	v_lshlrev_b32_e32 v254, 12, v254
	v_add_u32_e32 v236, 1, v236
	v_cndmask_b32_e32 v236, 0, v236, vcc
	v_lshl_add_u64 v[226:227], v[254:255], 0, v[248:249]
	v_lshl_add_u64 v[230:231], v[254:255], 0, v[250:251]
	v_add_u32_e32 v236, s8, v236
	v_mad_i64_i32 v[234:235], s[0:1], v236, s33, v[252:253]
	global_load_dwordx4 v[154:157], v[224:225], off
	global_load_dwordx4 v[116:119], v[232:233], off
	global_load_dwordx4 v[158:161], v[224:225], off offset:64
	global_load_dwordx4 v[120:123], v[232:233], off offset:64
	global_load_dwordx4 v[162:165], v[224:225], off offset:128
	global_load_dwordx4 v[124:127], v[232:233], off offset:128
	global_load_dwordx4 v[166:169], v[224:225], off offset:192
	global_load_dwordx4 v[134:137], v[232:233], off offset:192
	global_load_dwordx4 v[208:211], v[226:227], off
	global_load_dwordx4 v[138:141], v[234:235], off
	global_load_dwordx4 v[212:215], v[226:227], off offset:64
	global_load_dwordx4 v[200:203], v[234:235], off offset:64
	global_load_dwordx4 v[216:219], v[226:227], off offset:128
	global_load_dwordx4 v[92:95], v[234:235], off offset:128
	global_load_dwordx4 v[220:223], v[226:227], off offset:192
	global_load_dwordx4 v[244:247], v[234:235], off offset:192
	s_waitcnt vmcnt(0)
	v_pk_mul_f32 v[204:205], v[204:205], v[116:117]
	v_pk_mul_f32 v[206:207], v[206:207], v[118:119]
	v_pk_fma_f32 v[204:205], v[154:155], s[6:7], v[204:205] op_sel_hi:[1,0,1]
	v_pk_fma_f32 v[206:207], v[156:157], s[6:7], v[206:207] op_sel_hi:[1,0,1]
	global_store_dwordx4 v[228:229], v[204:207], off
	v_pk_mul_f32 v[88:89], v[88:89], v[120:121]
	v_pk_mul_f32 v[90:91], v[90:91], v[122:123]
	v_pk_fma_f32 v[88:89], v[158:159], s[6:7], v[88:89] op_sel_hi:[1,0,1]
	v_pk_fma_f32 v[90:91], v[160:161], s[6:7], v[90:91] op_sel_hi:[1,0,1]
	global_store_dwordx4 v[228:229], v[88:91], off offset:64
	v_pk_mul_f32 v[84:85], v[84:85], v[124:125]
	v_pk_mul_f32 v[86:87], v[86:87], v[126:127]
	v_pk_fma_f32 v[84:85], v[162:163], s[6:7], v[84:85] op_sel_hi:[1,0,1]
	v_pk_fma_f32 v[86:87], v[164:165], s[6:7], v[86:87] op_sel_hi:[1,0,1]
	global_store_dwordx4 v[228:229], v[84:87], off offset:128
	v_pk_mul_f32 v[80:81], v[80:81], v[134:135]
	v_pk_mul_f32 v[82:83], v[82:83], v[136:137]
	v_pk_fma_f32 v[80:81], v[166:167], s[6:7], v[80:81] op_sel_hi:[1,0,1]
	v_pk_fma_f32 v[82:83], v[168:169], s[6:7], v[82:83] op_sel_hi:[1,0,1]
	global_store_dwordx4 v[228:229], v[80:83], off offset:192
	v_pk_mul_f32 v[76:77], v[76:77], v[138:139]
	v_pk_mul_f32 v[78:79], v[78:79], v[140:141]
	v_pk_fma_f32 v[76:77], v[208:209], s[6:7], v[76:77] op_sel_hi:[1,0,1]
	v_pk_fma_f32 v[78:79], v[210:211], s[6:7], v[78:79] op_sel_hi:[1,0,1]
	global_store_dwordx4 v[230:231], v[76:79], off
	v_pk_mul_f32 v[72:73], v[72:73], v[200:201]
	v_pk_mul_f32 v[74:75], v[74:75], v[202:203]
	v_pk_fma_f32 v[72:73], v[212:213], s[6:7], v[72:73] op_sel_hi:[1,0,1]
	v_pk_fma_f32 v[74:75], v[214:215], s[6:7], v[74:75] op_sel_hi:[1,0,1]
	global_store_dwordx4 v[230:231], v[72:75], off offset:64
	v_pk_mul_f32 v[68:69], v[68:69], v[92:93]
	v_pk_mul_f32 v[70:71], v[70:71], v[94:95]
	v_pk_fma_f32 v[68:69], v[216:217], s[6:7], v[68:69] op_sel_hi:[1,0,1]
	v_pk_fma_f32 v[70:71], v[218:219], s[6:7], v[70:71] op_sel_hi:[1,0,1]
	global_store_dwordx4 v[230:231], v[68:71], off offset:128
	v_pk_mul_f32 v[64:65], v[64:65], v[244:245]
	v_pk_mul_f32 v[66:67], v[66:67], v[246:247]
	v_pk_fma_f32 v[64:65], v[220:221], s[6:7], v[64:65] op_sel_hi:[1,0,1]
	v_pk_fma_f32 v[66:67], v[222:223], s[6:7], v[66:67] op_sel_hi:[1,0,1]
	global_store_dwordx4 v[230:231], v[64:67], off offset:192
	v_add_u32_e32 v254, 32, v237
	v_add_u32_e32 v236, 0xfffff000, v254
	v_cmp_lt_i32_e32 vcc, 0xfff, v254
	v_lshrrev_b32_e32 v236, 10, v236
	v_lshlrev_b32_e32 v254, 12, v254
	v_add_u32_e32 v236, 1, v236
	v_cndmask_b32_e32 v236, 0, v236, vcc
	v_lshl_add_u64 v[224:225], v[254:255], 0, v[248:249]
	v_lshl_add_u64 v[228:229], v[254:255], 0, v[250:251]
	v_add_u32_e32 v236, s8, v236
	v_mad_i64_i32 v[232:233], s[0:1], v236, s33, v[252:253]
	v_add_u32_e32 v254, 48, v237
	v_add_u32_e32 v236, 0xfffff000, v254
	v_cmp_lt_i32_e32 vcc, 0xfff, v254
	v_lshrrev_b32_e32 v236, 10, v236
	v_lshlrev_b32_e32 v254, 12, v254
	v_add_u32_e32 v236, 1, v236
	v_cndmask_b32_e32 v236, 0, v236, vcc
	v_lshl_add_u64 v[226:227], v[254:255], 0, v[248:249]
	v_lshl_add_u64 v[230:231], v[254:255], 0, v[250:251]
	v_add_u32_e32 v236, s8, v236
	v_mad_i64_i32 v[234:235], s[0:1], v236, s33, v[252:253]
	global_load_dwordx4 v[154:157], v[224:225], off
	global_load_dwordx4 v[116:119], v[232:233], off
	global_load_dwordx4 v[158:161], v[224:225], off offset:64
	global_load_dwordx4 v[120:123], v[232:233], off offset:64
	global_load_dwordx4 v[162:165], v[224:225], off offset:128
	global_load_dwordx4 v[124:127], v[232:233], off offset:128
	global_load_dwordx4 v[166:169], v[224:225], off offset:192
	global_load_dwordx4 v[134:137], v[232:233], off offset:192
	global_load_dwordx4 v[208:211], v[226:227], off
	global_load_dwordx4 v[138:141], v[234:235], off
	global_load_dwordx4 v[212:215], v[226:227], off offset:64
	global_load_dwordx4 v[200:203], v[234:235], off offset:64
	global_load_dwordx4 v[216:219], v[226:227], off offset:128
	global_load_dwordx4 v[92:95], v[234:235], off offset:128
	global_load_dwordx4 v[220:223], v[226:227], off offset:192
	global_load_dwordx4 v[244:247], v[234:235], off offset:192
	s_waitcnt vmcnt(0)
	v_pk_mul_f32 v[60:61], v[60:61], v[116:117]
	v_pk_mul_f32 v[62:63], v[62:63], v[118:119]
	v_pk_fma_f32 v[60:61], v[154:155], s[6:7], v[60:61] op_sel_hi:[1,0,1]
	v_pk_fma_f32 v[62:63], v[156:157], s[6:7], v[62:63] op_sel_hi:[1,0,1]
	global_store_dwordx4 v[228:229], v[60:63], off
	v_pk_mul_f32 v[56:57], v[56:57], v[120:121]
	v_pk_mul_f32 v[58:59], v[58:59], v[122:123]
	v_pk_fma_f32 v[56:57], v[158:159], s[6:7], v[56:57] op_sel_hi:[1,0,1]
	v_pk_fma_f32 v[58:59], v[160:161], s[6:7], v[58:59] op_sel_hi:[1,0,1]
	global_store_dwordx4 v[228:229], v[56:59], off offset:64
	v_pk_mul_f32 v[52:53], v[52:53], v[124:125]
	v_pk_mul_f32 v[54:55], v[54:55], v[126:127]
	v_pk_fma_f32 v[52:53], v[162:163], s[6:7], v[52:53] op_sel_hi:[1,0,1]
	v_pk_fma_f32 v[54:55], v[164:165], s[6:7], v[54:55] op_sel_hi:[1,0,1]
	global_store_dwordx4 v[228:229], v[52:55], off offset:128
	v_pk_mul_f32 v[48:49], v[48:49], v[134:135]
	v_pk_mul_f32 v[50:51], v[50:51], v[136:137]
	v_pk_fma_f32 v[48:49], v[166:167], s[6:7], v[48:49] op_sel_hi:[1,0,1]
	v_pk_fma_f32 v[50:51], v[168:169], s[6:7], v[50:51] op_sel_hi:[1,0,1]
	global_store_dwordx4 v[228:229], v[48:51], off offset:192
	v_pk_mul_f32 v[44:45], v[44:45], v[138:139]
	v_pk_mul_f32 v[46:47], v[46:47], v[140:141]
	v_pk_fma_f32 v[44:45], v[208:209], s[6:7], v[44:45] op_sel_hi:[1,0,1]
	v_pk_fma_f32 v[46:47], v[210:211], s[6:7], v[46:47] op_sel_hi:[1,0,1]
	global_store_dwordx4 v[230:231], v[44:47], off
	v_pk_mul_f32 v[40:41], v[40:41], v[200:201]
	v_pk_mul_f32 v[42:43], v[42:43], v[202:203]
	v_pk_fma_f32 v[40:41], v[212:213], s[6:7], v[40:41] op_sel_hi:[1,0,1]
	v_pk_fma_f32 v[42:43], v[214:215], s[6:7], v[42:43] op_sel_hi:[1,0,1]
	global_store_dwordx4 v[230:231], v[40:43], off offset:64
	v_pk_mul_f32 v[36:37], v[36:37], v[92:93]
	v_pk_mul_f32 v[38:39], v[38:39], v[94:95]
	v_pk_fma_f32 v[36:37], v[216:217], s[6:7], v[36:37] op_sel_hi:[1,0,1]
	v_pk_fma_f32 v[38:39], v[218:219], s[6:7], v[38:39] op_sel_hi:[1,0,1]
	global_store_dwordx4 v[230:231], v[36:39], off offset:128
	v_pk_mul_f32 v[32:33], v[32:33], v[244:245]
	v_pk_mul_f32 v[34:35], v[34:35], v[246:247]
	v_pk_fma_f32 v[32:33], v[220:221], s[6:7], v[32:33] op_sel_hi:[1,0,1]
	v_pk_fma_f32 v[34:35], v[222:223], s[6:7], v[34:35] op_sel_hi:[1,0,1]
	global_store_dwordx4 v[230:231], v[32:35], off offset:192
	v_add_u32_e32 v254, 64, v237
	v_add_u32_e32 v236, 0xfffff000, v254
	v_cmp_lt_i32_e32 vcc, 0xfff, v254
	v_lshrrev_b32_e32 v236, 10, v236
	v_lshlrev_b32_e32 v254, 12, v254
	v_add_u32_e32 v236, 1, v236
	v_cndmask_b32_e32 v236, 0, v236, vcc
	v_lshl_add_u64 v[224:225], v[254:255], 0, v[248:249]
	v_lshl_add_u64 v[228:229], v[254:255], 0, v[250:251]
	v_add_u32_e32 v236, s8, v236
	v_mad_i64_i32 v[232:233], s[0:1], v236, s33, v[252:253]
	v_add_u32_e32 v254, 80, v237
	v_add_u32_e32 v236, 0xfffff000, v254
	v_cmp_lt_i32_e32 vcc, 0xfff, v254
	v_lshrrev_b32_e32 v236, 10, v236
	v_lshlrev_b32_e32 v254, 12, v254
	v_add_u32_e32 v236, 1, v236
	v_cndmask_b32_e32 v236, 0, v236, vcc
	v_lshl_add_u64 v[226:227], v[254:255], 0, v[248:249]
	v_lshl_add_u64 v[230:231], v[254:255], 0, v[250:251]
	v_add_u32_e32 v236, s8, v236
	v_mad_i64_i32 v[234:235], s[0:1], v236, s33, v[252:253]
	global_load_dwordx4 v[154:157], v[224:225], off
	global_load_dwordx4 v[116:119], v[232:233], off
	global_load_dwordx4 v[158:161], v[224:225], off offset:64
	global_load_dwordx4 v[120:123], v[232:233], off offset:64
	global_load_dwordx4 v[162:165], v[224:225], off offset:128
	global_load_dwordx4 v[124:127], v[232:233], off offset:128
	global_load_dwordx4 v[166:169], v[224:225], off offset:192
	global_load_dwordx4 v[134:137], v[232:233], off offset:192
	global_load_dwordx4 v[208:211], v[226:227], off
	global_load_dwordx4 v[138:141], v[234:235], off
	global_load_dwordx4 v[212:215], v[226:227], off offset:64
	global_load_dwordx4 v[200:203], v[234:235], off offset:64
	global_load_dwordx4 v[216:219], v[226:227], off offset:128
	global_load_dwordx4 v[92:95], v[234:235], off offset:128
	global_load_dwordx4 v[220:223], v[226:227], off offset:192
	global_load_dwordx4 v[244:247], v[234:235], off offset:192
	s_waitcnt vmcnt(0)
	v_pk_mul_f32 v[28:29], v[28:29], v[116:117]
	v_pk_mul_f32 v[30:31], v[30:31], v[118:119]
	v_pk_fma_f32 v[28:29], v[154:155], s[6:7], v[28:29] op_sel_hi:[1,0,1]
	v_pk_fma_f32 v[30:31], v[156:157], s[6:7], v[30:31] op_sel_hi:[1,0,1]
	global_store_dwordx4 v[228:229], v[28:31], off
	v_pk_mul_f32 v[24:25], v[24:25], v[120:121]
	v_pk_mul_f32 v[26:27], v[26:27], v[122:123]
	v_pk_fma_f32 v[24:25], v[158:159], s[6:7], v[24:25] op_sel_hi:[1,0,1]
	v_pk_fma_f32 v[26:27], v[160:161], s[6:7], v[26:27] op_sel_hi:[1,0,1]
	global_store_dwordx4 v[228:229], v[24:27], off offset:64
	v_pk_mul_f32 v[20:21], v[20:21], v[124:125]
	v_pk_mul_f32 v[22:23], v[22:23], v[126:127]
	v_pk_fma_f32 v[20:21], v[162:163], s[6:7], v[20:21] op_sel_hi:[1,0,1]
	v_pk_fma_f32 v[22:23], v[164:165], s[6:7], v[22:23] op_sel_hi:[1,0,1]
	global_store_dwordx4 v[228:229], v[20:23], off offset:128
	v_pk_mul_f32 v[16:17], v[16:17], v[134:135]
	v_pk_mul_f32 v[18:19], v[18:19], v[136:137]
	v_pk_fma_f32 v[16:17], v[166:167], s[6:7], v[16:17] op_sel_hi:[1,0,1]
	v_pk_fma_f32 v[18:19], v[168:169], s[6:7], v[18:19] op_sel_hi:[1,0,1]
	global_store_dwordx4 v[228:229], v[16:19], off offset:192
	v_pk_mul_f32 v[12:13], v[12:13], v[138:139]
	v_pk_mul_f32 v[14:15], v[14:15], v[140:141]
	v_pk_fma_f32 v[12:13], v[208:209], s[6:7], v[12:13] op_sel_hi:[1,0,1]
	v_pk_fma_f32 v[14:15], v[210:211], s[6:7], v[14:15] op_sel_hi:[1,0,1]
	global_store_dwordx4 v[230:231], v[12:15], off
	v_pk_mul_f32 v[8:9], v[8:9], v[200:201]
	v_pk_mul_f32 v[10:11], v[10:11], v[202:203]
	v_pk_fma_f32 v[8:9], v[212:213], s[6:7], v[8:9] op_sel_hi:[1,0,1]
	v_pk_fma_f32 v[10:11], v[214:215], s[6:7], v[10:11] op_sel_hi:[1,0,1]
	global_store_dwordx4 v[230:231], v[8:11], off offset:64
	v_pk_mul_f32 v[4:5], v[4:5], v[92:93]
	v_pk_mul_f32 v[6:7], v[6:7], v[94:95]
	v_pk_fma_f32 v[4:5], v[216:217], s[6:7], v[4:5] op_sel_hi:[1,0,1]
	v_pk_fma_f32 v[6:7], v[218:219], s[6:7], v[6:7] op_sel_hi:[1,0,1]
	global_store_dwordx4 v[230:231], v[4:7], off offset:128
	v_pk_mul_f32 v[0:1], v[0:1], v[244:245]
	v_pk_mul_f32 v[2:3], v[2:3], v[246:247]
	v_pk_fma_f32 v[0:1], v[220:221], s[6:7], v[0:1] op_sel_hi:[1,0,1]
	v_pk_fma_f32 v[2:3], v[222:223], s[6:7], v[2:3] op_sel_hi:[1,0,1]
	global_store_dwordx4 v[230:231], v[0:3], off offset:192
	s_branch .Lout_epi_done
.Lout_epi_ln:
	v_readlane_b32 s10, v243, 9
	v_readlane_b32 s11, v243, 10
	v_readlane_b32 s12, v242, 29
	v_readlane_b32 s13, v242, 30
	v_readlane_b32 s14, v243, 11
	v_readlane_b32 s15, v243, 12
	s_mov_b32 s6, 0x3fd744fd
	v_add_u32_e32 v236, s0, v145
	v_or_b32_e32 v254, s4, v146
	v_mov_b32_e32 v255, 0
	v_or_b32_e32 v237, v236, v133
	v_lshlrev_b64 v[254:255], 2, v[254:255]
	s_nop 0
	v_lshl_add_u64 v[250:251], s[12:13], 0, v[254:255]
	v_lshl_add_u64 v[252:253], s[14:15], 0, v[254:255]
	s_mov_b64 s[14:15], 0x2000
	v_lshl_add_u64 v[252:253], v[252:253], 0, s[14:15]
	v_readlane_b32 s12, v242, 25
	v_readlane_b32 s13, v242, 26
	v_lshl_add_u64 v[248:249], s[12:13], 0, v[254:255]
	v_readlane_b32 s12, v241, 9
	s_add_i32 s12, s12, -16
	s_mul_i32 s12, s12, 57
	s_lshr_b32 s12, s12, 9
	s_lshl_b32 s12, s12, 12
	v_readlane_b32 s14, v242, 3
	v_readlane_b32 s15, v242, 4
	s_add_u32 s14, s14, s12
	s_addc_u32 s15, s15, 0
	v_lshl_add_u64 v[224:225], s[14:15], 0, v[254:255]
	v_readlane_b32 s14, v242, 5
	v_readlane_b32 s15, v242, 6
	s_add_u32 s14, s14, s12
	s_addc_u32 s15, s15, 0
	v_lshl_add_u64 v[226:227], s[14:15], 0, v[254:255]
	global_load_dwordx4 v[96:99], v[224:225], off
	global_load_dwordx4 v[112:115], v[226:227], off
	global_load_dwordx4 v[100:103], v[224:225], off offset:64
	global_load_dwordx4 v[150:153], v[226:227], off offset:64
	global_load_dwordx4 v[104:107], v[224:225], off offset:128
	global_load_dwordx4 v[142:145], v[226:227], off offset:128
	global_load_dwordx4 v[108:111], v[224:225], off offset:192
	global_load_dwordx4 v[146:149], v[226:227], off offset:192
	v_mov_b32_e32 v255, 0
	v_add_u32_e32 v254, 0, v237
	v_add_u32_e32 v236, 0xfffff000, v254
	v_cmp_lt_i32_e32 vcc, 0xfff, v254
	v_lshrrev_b32_e32 v236, 10, v236
	v_lshlrev_b32_e32 v224, 3, v254
	v_lshlrev_b32_e32 v254, 12, v254
	v_add_u32_e32 v236, 1, v236
	v_mov_b32_e32 v225, 0
	v_cndmask_b32_e32 v236, 0, v236, vcc
	v_lshl_add_u64 v[224:225], v[224:225], 0, s[10:11]
	v_lshl_add_u64 v[228:229], v[254:255], 0, v[250:251]
	v_add_u32_e32 v236, s8, v236
	v_mad_i64_i32 v[232:233], s[0:1], v236, s33, v[252:253]
	global_load_dwordx2 v[132:133], v[224:225], off
	v_lshl_add_u64 v[224:225], v[254:255], 0, v[248:249]
	v_add_u32_e32 v254, 16, v237
	v_add_u32_e32 v236, 0xfffff000, v254
	v_cmp_lt_i32_e32 vcc, 0xfff, v254
	v_lshrrev_b32_e32 v236, 10, v236
	v_lshlrev_b32_e32 v226, 3, v254
	v_lshlrev_b32_e32 v254, 12, v254
	v_add_u32_e32 v236, 1, v236
	v_mov_b32_e32 v227, 0
	v_cndmask_b32_e32 v236, 0, v236, vcc
	v_lshl_add_u64 v[226:227], v[226:227], 0, s[10:11]
	v_lshl_add_u64 v[230:231], v[254:255], 0, v[250:251]
	v_add_u32_e32 v236, s8, v236
	v_mad_i64_i32 v[234:235], s[0:1], v236, s33, v[252:253]
	global_load_dword v128, v[226:227], off
	global_load_dword v170, v[226:227], off offset:4
	v_lshl_add_u64 v[226:227], v[254:255], 0, v[248:249]
	global_load_dwordx4 v[154:157], v[224:225], off
	global_load_dwordx4 v[116:119], v[232:233], off
	global_load_dwordx4 v[158:161], v[224:225], off offset:64
	global_load_dwordx4 v[120:123], v[232:233], off offset:64
	global_load_dwordx4 v[162:165], v[224:225], off offset:128
	global_load_dwordx4 v[124:127], v[232:233], off offset:128
	global_load_dwordx4 v[166:169], v[224:225], off offset:192
	global_load_dwordx4 v[134:137], v[232:233], off offset:192
	global_load_dwordx4 v[208:211], v[226:227], off
	global_load_dwordx4 v[138:141], v[234:235], off
	global_load_dwordx4 v[212:215], v[226:227], off offset:64
	global_load_dwordx4 v[200:203], v[234:235], off offset:64
	global_load_dwordx4 v[216:219], v[226:227], off offset:128
	global_load_dwordx4 v[92:95], v[234:235], off offset:128
	global_load_dwordx4 v[220:223], v[226:227], off offset:192
	global_load_dwordx4 v[244:247], v[234:235], off offset:192
	s_waitcnt vmcnt(0)
	v_pk_mul_f32 v[204:205], v[204:205], v[116:117]
	v_pk_add_f32 v[154:155], v[154:155], v[132:133] op_sel_hi:[1,0] neg_lo:[0,1] neg_hi:[0,1]
	v_pk_mul_f32 v[206:207], v[206:207], v[118:119]
	v_pk_add_f32 v[156:157], v[156:157], v[132:133] op_sel_hi:[1,0] neg_lo:[0,1] neg_hi:[0,1]
	v_pk_mul_f32 v[154:155], v[154:155], v[132:133] op_sel:[0,1] op_sel_hi:[1,1]
	v_pk_mul_f32 v[156:157], v[156:157], v[132:133] op_sel:[0,1] op_sel_hi:[1,1]
	v_pk_fma_f32 v[154:155], v[96:97], v[154:155], v[112:113]
	v_pk_fma_f32 v[156:157], v[98:99], v[156:157], v[114:115]
	v_pk_fma_f32 v[204:205], v[154:155], s[6:7], v[204:205] op_sel_hi:[1,0,1]
	v_pk_fma_f32 v[206:207], v[156:157], s[6:7], v[206:207] op_sel_hi:[1,0,1]
	global_store_dwordx4 v[228:229], v[204:207], off
	v_pk_mul_f32 v[88:89], v[88:89], v[120:121]
	v_pk_add_f32 v[158:159], v[158:159], v[132:133] op_sel_hi:[1,0] neg_lo:[0,1] neg_hi:[0,1]
	v_pk_mul_f32 v[90:91], v[90:91], v[122:123]
	v_pk_add_f32 v[160:161], v[160:161], v[132:133] op_sel_hi:[1,0] neg_lo:[0,1] neg_hi:[0,1]
	v_pk_mul_f32 v[158:159], v[158:159], v[132:133] op_sel:[0,1] op_sel_hi:[1,1]
	v_pk_mul_f32 v[160:161], v[160:161], v[132:133] op_sel:[0,1] op_sel_hi:[1,1]
	v_pk_fma_f32 v[158:159], v[100:101], v[158:159], v[150:151]
	v_pk_fma_f32 v[160:161], v[102:103], v[160:161], v[152:153]
	v_pk_fma_f32 v[88:89], v[158:159], s[6:7], v[88:89] op_sel_hi:[1,0,1]
	v_pk_fma_f32 v[90:91], v[160:161], s[6:7], v[90:91] op_sel_hi:[1,0,1]
	global_store_dwordx4 v[228:229], v[88:91], off offset:64
	v_pk_mul_f32 v[84:85], v[84:85], v[124:125]
	v_pk_add_f32 v[162:163], v[162:163], v[132:133] op_sel_hi:[1,0] neg_lo:[0,1] neg_hi:[0,1]
	v_pk_mul_f32 v[86:87], v[86:87], v[126:127]
	v_pk_add_f32 v[164:165], v[164:165], v[132:133] op_sel_hi:[1,0] neg_lo:[0,1] neg_hi:[0,1]
	v_pk_mul_f32 v[162:163], v[162:163], v[132:133] op_sel:[0,1] op_sel_hi:[1,1]
	v_pk_mul_f32 v[164:165], v[164:165], v[132:133] op_sel:[0,1] op_sel_hi:[1,1]
	v_pk_fma_f32 v[162:163], v[104:105], v[162:163], v[142:143]
	v_pk_fma_f32 v[164:165], v[106:107], v[164:165], v[144:145]
	v_pk_fma_f32 v[84:85], v[162:163], s[6:7], v[84:85] op_sel_hi:[1,0,1]
	v_pk_fma_f32 v[86:87], v[164:165], s[6:7], v[86:87] op_sel_hi:[1,0,1]
	global_store_dwordx4 v[228:229], v[84:87], off offset:128
	v_pk_mul_f32 v[80:81], v[80:81], v[134:135]
	v_pk_add_f32 v[166:167], v[166:167], v[132:133] op_sel_hi:[1,0] neg_lo:[0,1] neg_hi:[0,1]
	v_pk_mul_f32 v[82:83], v[82:83], v[136:137]
	v_pk_add_f32 v[168:169], v[168:169], v[132:133] op_sel_hi:[1,0] neg_lo:[0,1] neg_hi:[0,1]
	v_pk_mul_f32 v[166:167], v[166:167], v[132:133] op_sel:[0,1] op_sel_hi:[1,1]
	v_pk_mul_f32 v[168:169], v[168:169], v[132:133] op_sel:[0,1] op_sel_hi:[1,1]
	v_pk_fma_f32 v[166:167], v[108:109], v[166:167], v[146:147]
	v_pk_fma_f32 v[168:169], v[110:111], v[168:169], v[148:149]
	v_pk_fma_f32 v[80:81], v[166:167], s[6:7], v[80:81] op_sel_hi:[1,0,1]
	v_pk_fma_f32 v[82:83], v[168:169], s[6:7], v[82:83] op_sel_hi:[1,0,1]
	global_store_dwordx4 v[228:229], v[80:83], off offset:192
	v_pk_mul_f32 v[76:77], v[76:77], v[138:139]
	v_pk_add_f32 v[208:209], v[208:209], v[128:129] op_sel_hi:[1,0] neg_lo:[0,1] neg_hi:[0,1]
	v_pk_mul_f32 v[78:79], v[78:79], v[140:141]
	v_pk_add_f32 v[210:211], v[210:211], v[128:129] op_sel_hi:[1,0] neg_lo:[0,1] neg_hi:[0,1]
	v_pk_mul_f32 v[208:209], v[208:209], v[170:171] op_sel_hi:[1,0]
	v_pk_mul_f32 v[210:211], v[210:211], v[170:171] op_sel_hi:[1,0]
	v_pk_fma_f32 v[208:209], v[96:97], v[208:209], v[112:113]
	v_pk_fma_f32 v[210:211], v[98:99], v[210:211], v[114:115]
	v_pk_fma_f32 v[76:77], v[208:209], s[6:7], v[76:77] op_sel_hi:[1,0,1]
	v_pk_fma_f32 v[78:79], v[210:211], s[6:7], v[78:79] op_sel_hi:[1,0,1]
	global_store_dwordx4 v[230:231], v[76:79], off
	v_pk_mul_f32 v[72:73], v[72:73], v[200:201]
	v_pk_add_f32 v[212:213], v[212:213], v[128:129] op_sel_hi:[1,0] neg_lo:[0,1] neg_hi:[0,1]
	v_pk_mul_f32 v[74:75], v[74:75], v[202:203]
	v_pk_add_f32 v[214:215], v[214:215], v[128:129] op_sel_hi:[1,0] neg_lo:[0,1] neg_hi:[0,1]
	v_pk_mul_f32 v[212:213], v[212:213], v[170:171] op_sel_hi:[1,0]
	v_pk_mul_f32 v[214:215], v[214:215], v[170:171] op_sel_hi:[1,0]
	v_pk_fma_f32 v[212:213], v[100:101], v[212:213], v[150:151]
	v_pk_fma_f32 v[214:215], v[102:103], v[214:215], v[152:153]
	v_pk_fma_f32 v[72:73], v[212:213], s[6:7], v[72:73] op_sel_hi:[1,0,1]
	v_pk_fma_f32 v[74:75], v[214:215], s[6:7], v[74:75] op_sel_hi:[1,0,1]
	global_store_dwordx4 v[230:231], v[72:75], off offset:64
	v_pk_mul_f32 v[68:69], v[68:69], v[92:93]
	v_pk_add_f32 v[216:217], v[216:217], v[128:129] op_sel_hi:[1,0] neg_lo:[0,1] neg_hi:[0,1]
	v_pk_mul_f32 v[70:71], v[70:71], v[94:95]
	v_pk_add_f32 v[218:219], v[218:219], v[128:129] op_sel_hi:[1,0] neg_lo:[0,1] neg_hi:[0,1]
	v_pk_mul_f32 v[216:217], v[216:217], v[170:171] op_sel_hi:[1,0]
	v_pk_mul_f32 v[218:219], v[218:219], v[170:171] op_sel_hi:[1,0]
	v_pk_fma_f32 v[216:217], v[104:105], v[216:217], v[142:143]
	v_pk_fma_f32 v[218:219], v[106:107], v[218:219], v[144:145]
	v_pk_fma_f32 v[68:69], v[216:217], s[6:7], v[68:69] op_sel_hi:[1,0,1]
	v_pk_fma_f32 v[70:71], v[218:219], s[6:7], v[70:71] op_sel_hi:[1,0,1]
	global_store_dwordx4 v[230:231], v[68:71], off offset:128
	v_pk_mul_f32 v[64:65], v[64:65], v[244:245]
	v_pk_add_f32 v[220:221], v[220:221], v[128:129] op_sel_hi:[1,0] neg_lo:[0,1] neg_hi:[0,1]
	v_pk_mul_f32 v[66:67], v[66:67], v[246:247]
	v_pk_add_f32 v[222:223], v[222:223], v[128:129] op_sel_hi:[1,0] neg_lo:[0,1] neg_hi:[0,1]
	v_pk_mul_f32 v[220:221], v[220:221], v[170:171] op_sel_hi:[1,0]
	v_pk_mul_f32 v[222:223], v[222:223], v[170:171] op_sel_hi:[1,0]
	v_pk_fma_f32 v[220:221], v[108:109], v[220:221], v[146:147]
	v_pk_fma_f32 v[222:223], v[110:111], v[222:223], v[148:149]
	v_pk_fma_f32 v[64:65], v[220:221], s[6:7], v[64:65] op_sel_hi:[1,0,1]
	v_pk_fma_f32 v[66:67], v[222:223], s[6:7], v[66:67] op_sel_hi:[1,0,1]
	global_store_dwordx4 v[230:231], v[64:67], off offset:192
	v_add_u32_e32 v254, 32, v237
	v_add_u32_e32 v236, 0xfffff000, v254
	v_cmp_lt_i32_e32 vcc, 0xfff, v254
	v_lshrrev_b32_e32 v236, 10, v236
	v_lshlrev_b32_e32 v224, 3, v254
	v_lshlrev_b32_e32 v254, 12, v254
	v_add_u32_e32 v236, 1, v236
	v_mov_b32_e32 v225, 0
	v_cndmask_b32_e32 v236, 0, v236, vcc
	v_lshl_add_u64 v[224:225], v[224:225], 0, s[10:11]
	v_lshl_add_u64 v[228:229], v[254:255], 0, v[250:251]
	v_add_u32_e32 v236, s8, v236
	v_mad_i64_i32 v[232:233], s[0:1], v236, s33, v[252:253]
	global_load_dwordx2 v[132:133], v[224:225], off
	v_lshl_add_u64 v[224:225], v[254:255], 0, v[248:249]
	v_add_u32_e32 v254, 48, v237
	v_add_u32_e32 v236, 0xfffff000, v254
	v_cmp_lt_i32_e32 vcc, 0xfff, v254
	v_lshrrev_b32_e32 v236, 10, v236
	v_lshlrev_b32_e32 v226, 3, v254
	v_lshlrev_b32_e32 v254, 12, v254
	v_add_u32_e32 v236, 1, v236
	v_mov_b32_e32 v227, 0
	v_cndmask_b32_e32 v236, 0, v236, vcc
	v_lshl_add_u64 v[226:227], v[226:227], 0, s[10:11]
	v_lshl_add_u64 v[230:231], v[254:255], 0, v[250:251]
	v_add_u32_e32 v236, s8, v236
	v_mad_i64_i32 v[234:235], s[0:1], v236, s33, v[252:253]
	global_load_dword v128, v[226:227], off
	global_load_dword v170, v[226:227], off offset:4
	v_lshl_add_u64 v[226:227], v[254:255], 0, v[248:249]
	global_load_dwordx4 v[154:157], v[224:225], off
	global_load_dwordx4 v[116:119], v[232:233], off
	global_load_dwordx4 v[158:161], v[224:225], off offset:64
	global_load_dwordx4 v[120:123], v[232:233], off offset:64
	global_load_dwordx4 v[162:165], v[224:225], off offset:128
	global_load_dwordx4 v[124:127], v[232:233], off offset:128
	global_load_dwordx4 v[166:169], v[224:225], off offset:192
	global_load_dwordx4 v[134:137], v[232:233], off offset:192
	global_load_dwordx4 v[208:211], v[226:227], off
	global_load_dwordx4 v[138:141], v[234:235], off
	global_load_dwordx4 v[212:215], v[226:227], off offset:64
	global_load_dwordx4 v[200:203], v[234:235], off offset:64
	global_load_dwordx4 v[216:219], v[226:227], off offset:128
	global_load_dwordx4 v[92:95], v[234:235], off offset:128
	global_load_dwordx4 v[220:223], v[226:227], off offset:192
	global_load_dwordx4 v[244:247], v[234:235], off offset:192
	s_waitcnt vmcnt(0)
	v_pk_mul_f32 v[60:61], v[60:61], v[116:117]
	v_pk_add_f32 v[154:155], v[154:155], v[132:133] op_sel_hi:[1,0] neg_lo:[0,1] neg_hi:[0,1]
	v_pk_mul_f32 v[62:63], v[62:63], v[118:119]
	v_pk_add_f32 v[156:157], v[156:157], v[132:133] op_sel_hi:[1,0] neg_lo:[0,1] neg_hi:[0,1]
	v_pk_mul_f32 v[154:155], v[154:155], v[132:133] op_sel:[0,1] op_sel_hi:[1,1]
	v_pk_mul_f32 v[156:157], v[156:157], v[132:133] op_sel:[0,1] op_sel_hi:[1,1]
	v_pk_fma_f32 v[154:155], v[96:97], v[154:155], v[112:113]
	v_pk_fma_f32 v[156:157], v[98:99], v[156:157], v[114:115]
	v_pk_fma_f32 v[60:61], v[154:155], s[6:7], v[60:61] op_sel_hi:[1,0,1]
	v_pk_fma_f32 v[62:63], v[156:157], s[6:7], v[62:63] op_sel_hi:[1,0,1]
	global_store_dwordx4 v[228:229], v[60:63], off
	v_pk_mul_f32 v[56:57], v[56:57], v[120:121]
	v_pk_add_f32 v[158:159], v[158:159], v[132:133] op_sel_hi:[1,0] neg_lo:[0,1] neg_hi:[0,1]
	v_pk_mul_f32 v[58:59], v[58:59], v[122:123]
	v_pk_add_f32 v[160:161], v[160:161], v[132:133] op_sel_hi:[1,0] neg_lo:[0,1] neg_hi:[0,1]
	v_pk_mul_f32 v[158:159], v[158:159], v[132:133] op_sel:[0,1] op_sel_hi:[1,1]
	v_pk_mul_f32 v[160:161], v[160:161], v[132:133] op_sel:[0,1] op_sel_hi:[1,1]
	v_pk_fma_f32 v[158:159], v[100:101], v[158:159], v[150:151]
	v_pk_fma_f32 v[160:161], v[102:103], v[160:161], v[152:153]
	v_pk_fma_f32 v[56:57], v[158:159], s[6:7], v[56:57] op_sel_hi:[1,0,1]
	v_pk_fma_f32 v[58:59], v[160:161], s[6:7], v[58:59] op_sel_hi:[1,0,1]
	global_store_dwordx4 v[228:229], v[56:59], off offset:64
	v_pk_mul_f32 v[52:53], v[52:53], v[124:125]
	v_pk_add_f32 v[162:163], v[162:163], v[132:133] op_sel_hi:[1,0] neg_lo:[0,1] neg_hi:[0,1]
	v_pk_mul_f32 v[54:55], v[54:55], v[126:127]
	v_pk_add_f32 v[164:165], v[164:165], v[132:133] op_sel_hi:[1,0] neg_lo:[0,1] neg_hi:[0,1]
	v_pk_mul_f32 v[162:163], v[162:163], v[132:133] op_sel:[0,1] op_sel_hi:[1,1]
	v_pk_mul_f32 v[164:165], v[164:165], v[132:133] op_sel:[0,1] op_sel_hi:[1,1]
	v_pk_fma_f32 v[162:163], v[104:105], v[162:163], v[142:143]
	v_pk_fma_f32 v[164:165], v[106:107], v[164:165], v[144:145]
	v_pk_fma_f32 v[52:53], v[162:163], s[6:7], v[52:53] op_sel_hi:[1,0,1]
	v_pk_fma_f32 v[54:55], v[164:165], s[6:7], v[54:55] op_sel_hi:[1,0,1]
	global_store_dwordx4 v[228:229], v[52:55], off offset:128
	v_pk_mul_f32 v[48:49], v[48:49], v[134:135]
	v_pk_add_f32 v[166:167], v[166:167], v[132:133] op_sel_hi:[1,0] neg_lo:[0,1] neg_hi:[0,1]
	v_pk_mul_f32 v[50:51], v[50:51], v[136:137]
	v_pk_add_f32 v[168:169], v[168:169], v[132:133] op_sel_hi:[1,0] neg_lo:[0,1] neg_hi:[0,1]
	v_pk_mul_f32 v[166:167], v[166:167], v[132:133] op_sel:[0,1] op_sel_hi:[1,1]
	v_pk_mul_f32 v[168:169], v[168:169], v[132:133] op_sel:[0,1] op_sel_hi:[1,1]
	v_pk_fma_f32 v[166:167], v[108:109], v[166:167], v[146:147]
	v_pk_fma_f32 v[168:169], v[110:111], v[168:169], v[148:149]
	v_pk_fma_f32 v[48:49], v[166:167], s[6:7], v[48:49] op_sel_hi:[1,0,1]
	v_pk_fma_f32 v[50:51], v[168:169], s[6:7], v[50:51] op_sel_hi:[1,0,1]
	global_store_dwordx4 v[228:229], v[48:51], off offset:192
	v_pk_mul_f32 v[44:45], v[44:45], v[138:139]
	v_pk_add_f32 v[208:209], v[208:209], v[128:129] op_sel_hi:[1,0] neg_lo:[0,1] neg_hi:[0,1]
	v_pk_mul_f32 v[46:47], v[46:47], v[140:141]
	v_pk_add_f32 v[210:211], v[210:211], v[128:129] op_sel_hi:[1,0] neg_lo:[0,1] neg_hi:[0,1]
	v_pk_mul_f32 v[208:209], v[208:209], v[170:171] op_sel_hi:[1,0]
	v_pk_mul_f32 v[210:211], v[210:211], v[170:171] op_sel_hi:[1,0]
	v_pk_fma_f32 v[208:209], v[96:97], v[208:209], v[112:113]
	v_pk_fma_f32 v[210:211], v[98:99], v[210:211], v[114:115]
	v_pk_fma_f32 v[44:45], v[208:209], s[6:7], v[44:45] op_sel_hi:[1,0,1]
	v_pk_fma_f32 v[46:47], v[210:211], s[6:7], v[46:47] op_sel_hi:[1,0,1]
	global_store_dwordx4 v[230:231], v[44:47], off
	v_pk_mul_f32 v[40:41], v[40:41], v[200:201]
	v_pk_add_f32 v[212:213], v[212:213], v[128:129] op_sel_hi:[1,0] neg_lo:[0,1] neg_hi:[0,1]
	v_pk_mul_f32 v[42:43], v[42:43], v[202:203]
	v_pk_add_f32 v[214:215], v[214:215], v[128:129] op_sel_hi:[1,0] neg_lo:[0,1] neg_hi:[0,1]
	v_pk_mul_f32 v[212:213], v[212:213], v[170:171] op_sel_hi:[1,0]
	v_pk_mul_f32 v[214:215], v[214:215], v[170:171] op_sel_hi:[1,0]
	v_pk_fma_f32 v[212:213], v[100:101], v[212:213], v[150:151]
	v_pk_fma_f32 v[214:215], v[102:103], v[214:215], v[152:153]
	v_pk_fma_f32 v[40:41], v[212:213], s[6:7], v[40:41] op_sel_hi:[1,0,1]
	v_pk_fma_f32 v[42:43], v[214:215], s[6:7], v[42:43] op_sel_hi:[1,0,1]
	global_store_dwordx4 v[230:231], v[40:43], off offset:64
	v_pk_mul_f32 v[36:37], v[36:37], v[92:93]
	v_pk_add_f32 v[216:217], v[216:217], v[128:129] op_sel_hi:[1,0] neg_lo:[0,1] neg_hi:[0,1]
	v_pk_mul_f32 v[38:39], v[38:39], v[94:95]
	v_pk_add_f32 v[218:219], v[218:219], v[128:129] op_sel_hi:[1,0] neg_lo:[0,1] neg_hi:[0,1]
	v_pk_mul_f32 v[216:217], v[216:217], v[170:171] op_sel_hi:[1,0]
	v_pk_mul_f32 v[218:219], v[218:219], v[170:171] op_sel_hi:[1,0]
	v_pk_fma_f32 v[216:217], v[104:105], v[216:217], v[142:143]
	v_pk_fma_f32 v[218:219], v[106:107], v[218:219], v[144:145]
	v_pk_fma_f32 v[36:37], v[216:217], s[6:7], v[36:37] op_sel_hi:[1,0,1]
	v_pk_fma_f32 v[38:39], v[218:219], s[6:7], v[38:39] op_sel_hi:[1,0,1]
	global_store_dwordx4 v[230:231], v[36:39], off offset:128
	v_pk_mul_f32 v[32:33], v[32:33], v[244:245]
	v_pk_add_f32 v[220:221], v[220:221], v[128:129] op_sel_hi:[1,0] neg_lo:[0,1] neg_hi:[0,1]
	v_pk_mul_f32 v[34:35], v[34:35], v[246:247]
	v_pk_add_f32 v[222:223], v[222:223], v[128:129] op_sel_hi:[1,0] neg_lo:[0,1] neg_hi:[0,1]
	v_pk_mul_f32 v[220:221], v[220:221], v[170:171] op_sel_hi:[1,0]
	v_pk_mul_f32 v[222:223], v[222:223], v[170:171] op_sel_hi:[1,0]
	v_pk_fma_f32 v[220:221], v[108:109], v[220:221], v[146:147]
	v_pk_fma_f32 v[222:223], v[110:111], v[222:223], v[148:149]
	v_pk_fma_f32 v[32:33], v[220:221], s[6:7], v[32:33] op_sel_hi:[1,0,1]
	v_pk_fma_f32 v[34:35], v[222:223], s[6:7], v[34:35] op_sel_hi:[1,0,1]
	global_store_dwordx4 v[230:231], v[32:35], off offset:192
	v_add_u32_e32 v254, 64, v237
	v_add_u32_e32 v236, 0xfffff000, v254
	v_cmp_lt_i32_e32 vcc, 0xfff, v254
	v_lshrrev_b32_e32 v236, 10, v236
	v_lshlrev_b32_e32 v224, 3, v254
	v_lshlrev_b32_e32 v254, 12, v254
	v_add_u32_e32 v236, 1, v236
	v_mov_b32_e32 v225, 0
	v_cndmask_b32_e32 v236, 0, v236, vcc
	v_lshl_add_u64 v[224:225], v[224:225], 0, s[10:11]
	v_lshl_add_u64 v[228:229], v[254:255], 0, v[250:251]
	v_add_u32_e32 v236, s8, v236
	v_mad_i64_i32 v[232:233], s[0:1], v236, s33, v[252:253]
	global_load_dwordx2 v[132:133], v[224:225], off
	v_lshl_add_u64 v[224:225], v[254:255], 0, v[248:249]
	v_add_u32_e32 v254, 80, v237
	v_add_u32_e32 v236, 0xfffff000, v254
	v_cmp_lt_i32_e32 vcc, 0xfff, v254
	v_lshrrev_b32_e32 v236, 10, v236
	v_lshlrev_b32_e32 v226, 3, v254
	v_lshlrev_b32_e32 v254, 12, v254
	v_add_u32_e32 v236, 1, v236
	v_mov_b32_e32 v227, 0
	v_cndmask_b32_e32 v236, 0, v236, vcc
	v_lshl_add_u64 v[226:227], v[226:227], 0, s[10:11]
	v_lshl_add_u64 v[230:231], v[254:255], 0, v[250:251]
	v_add_u32_e32 v236, s8, v236
	v_mad_i64_i32 v[234:235], s[0:1], v236, s33, v[252:253]
	global_load_dword v128, v[226:227], off
	global_load_dword v170, v[226:227], off offset:4
	v_lshl_add_u64 v[226:227], v[254:255], 0, v[248:249]
	global_load_dwordx4 v[154:157], v[224:225], off
	global_load_dwordx4 v[116:119], v[232:233], off
	global_load_dwordx4 v[158:161], v[224:225], off offset:64
	global_load_dwordx4 v[120:123], v[232:233], off offset:64
	global_load_dwordx4 v[162:165], v[224:225], off offset:128
	global_load_dwordx4 v[124:127], v[232:233], off offset:128
	global_load_dwordx4 v[166:169], v[224:225], off offset:192
	global_load_dwordx4 v[134:137], v[232:233], off offset:192
	global_load_dwordx4 v[208:211], v[226:227], off
	global_load_dwordx4 v[138:141], v[234:235], off
	global_load_dwordx4 v[212:215], v[226:227], off offset:64
	global_load_dwordx4 v[200:203], v[234:235], off offset:64
	global_load_dwordx4 v[216:219], v[226:227], off offset:128
	global_load_dwordx4 v[92:95], v[234:235], off offset:128
	global_load_dwordx4 v[220:223], v[226:227], off offset:192
	global_load_dwordx4 v[244:247], v[234:235], off offset:192
	s_waitcnt vmcnt(0)
	v_pk_mul_f32 v[28:29], v[28:29], v[116:117]
	v_pk_add_f32 v[154:155], v[154:155], v[132:133] op_sel_hi:[1,0] neg_lo:[0,1] neg_hi:[0,1]
	v_pk_mul_f32 v[30:31], v[30:31], v[118:119]
	v_pk_add_f32 v[156:157], v[156:157], v[132:133] op_sel_hi:[1,0] neg_lo:[0,1] neg_hi:[0,1]
	v_pk_mul_f32 v[154:155], v[154:155], v[132:133] op_sel:[0,1] op_sel_hi:[1,1]
	v_pk_mul_f32 v[156:157], v[156:157], v[132:133] op_sel:[0,1] op_sel_hi:[1,1]
	v_pk_fma_f32 v[154:155], v[96:97], v[154:155], v[112:113]
	v_pk_fma_f32 v[156:157], v[98:99], v[156:157], v[114:115]
	v_pk_fma_f32 v[28:29], v[154:155], s[6:7], v[28:29] op_sel_hi:[1,0,1]
	v_pk_fma_f32 v[30:31], v[156:157], s[6:7], v[30:31] op_sel_hi:[1,0,1]
	global_store_dwordx4 v[228:229], v[28:31], off
	v_pk_mul_f32 v[24:25], v[24:25], v[120:121]
	v_pk_add_f32 v[158:159], v[158:159], v[132:133] op_sel_hi:[1,0] neg_lo:[0,1] neg_hi:[0,1]
	v_pk_mul_f32 v[26:27], v[26:27], v[122:123]
	v_pk_add_f32 v[160:161], v[160:161], v[132:133] op_sel_hi:[1,0] neg_lo:[0,1] neg_hi:[0,1]
	v_pk_mul_f32 v[158:159], v[158:159], v[132:133] op_sel:[0,1] op_sel_hi:[1,1]
	v_pk_mul_f32 v[160:161], v[160:161], v[132:133] op_sel:[0,1] op_sel_hi:[1,1]
	v_pk_fma_f32 v[158:159], v[100:101], v[158:159], v[150:151]
	v_pk_fma_f32 v[160:161], v[102:103], v[160:161], v[152:153]
	v_pk_fma_f32 v[24:25], v[158:159], s[6:7], v[24:25] op_sel_hi:[1,0,1]
	v_pk_fma_f32 v[26:27], v[160:161], s[6:7], v[26:27] op_sel_hi:[1,0,1]
	global_store_dwordx4 v[228:229], v[24:27], off offset:64
	v_pk_mul_f32 v[20:21], v[20:21], v[124:125]
	v_pk_add_f32 v[162:163], v[162:163], v[132:133] op_sel_hi:[1,0] neg_lo:[0,1] neg_hi:[0,1]
	v_pk_mul_f32 v[22:23], v[22:23], v[126:127]
	v_pk_add_f32 v[164:165], v[164:165], v[132:133] op_sel_hi:[1,0] neg_lo:[0,1] neg_hi:[0,1]
	v_pk_mul_f32 v[162:163], v[162:163], v[132:133] op_sel:[0,1] op_sel_hi:[1,1]
	v_pk_mul_f32 v[164:165], v[164:165], v[132:133] op_sel:[0,1] op_sel_hi:[1,1]
	v_pk_fma_f32 v[162:163], v[104:105], v[162:163], v[142:143]
	v_pk_fma_f32 v[164:165], v[106:107], v[164:165], v[144:145]
	v_pk_fma_f32 v[20:21], v[162:163], s[6:7], v[20:21] op_sel_hi:[1,0,1]
	v_pk_fma_f32 v[22:23], v[164:165], s[6:7], v[22:23] op_sel_hi:[1,0,1]
	global_store_dwordx4 v[228:229], v[20:23], off offset:128
	v_pk_mul_f32 v[16:17], v[16:17], v[134:135]
	v_pk_add_f32 v[166:167], v[166:167], v[132:133] op_sel_hi:[1,0] neg_lo:[0,1] neg_hi:[0,1]
	v_pk_mul_f32 v[18:19], v[18:19], v[136:137]
	v_pk_add_f32 v[168:169], v[168:169], v[132:133] op_sel_hi:[1,0] neg_lo:[0,1] neg_hi:[0,1]
	v_pk_mul_f32 v[166:167], v[166:167], v[132:133] op_sel:[0,1] op_sel_hi:[1,1]
	v_pk_mul_f32 v[168:169], v[168:169], v[132:133] op_sel:[0,1] op_sel_hi:[1,1]
	v_pk_fma_f32 v[166:167], v[108:109], v[166:167], v[146:147]
	v_pk_fma_f32 v[168:169], v[110:111], v[168:169], v[148:149]
	v_pk_fma_f32 v[16:17], v[166:167], s[6:7], v[16:17] op_sel_hi:[1,0,1]
	v_pk_fma_f32 v[18:19], v[168:169], s[6:7], v[18:19] op_sel_hi:[1,0,1]
	global_store_dwordx4 v[228:229], v[16:19], off offset:192
	v_pk_mul_f32 v[12:13], v[12:13], v[138:139]
	v_pk_add_f32 v[208:209], v[208:209], v[128:129] op_sel_hi:[1,0] neg_lo:[0,1] neg_hi:[0,1]
	v_pk_mul_f32 v[14:15], v[14:15], v[140:141]
	v_pk_add_f32 v[210:211], v[210:211], v[128:129] op_sel_hi:[1,0] neg_lo:[0,1] neg_hi:[0,1]
	v_pk_mul_f32 v[208:209], v[208:209], v[170:171] op_sel_hi:[1,0]
	v_pk_mul_f32 v[210:211], v[210:211], v[170:171] op_sel_hi:[1,0]
	v_pk_fma_f32 v[208:209], v[96:97], v[208:209], v[112:113]
	v_pk_fma_f32 v[210:211], v[98:99], v[210:211], v[114:115]
	v_pk_fma_f32 v[12:13], v[208:209], s[6:7], v[12:13] op_sel_hi:[1,0,1]
	v_pk_fma_f32 v[14:15], v[210:211], s[6:7], v[14:15] op_sel_hi:[1,0,1]
	global_store_dwordx4 v[230:231], v[12:15], off
	v_pk_mul_f32 v[8:9], v[8:9], v[200:201]
	v_pk_add_f32 v[212:213], v[212:213], v[128:129] op_sel_hi:[1,0] neg_lo:[0,1] neg_hi:[0,1]
	v_pk_mul_f32 v[10:11], v[10:11], v[202:203]
	v_pk_add_f32 v[214:215], v[214:215], v[128:129] op_sel_hi:[1,0] neg_lo:[0,1] neg_hi:[0,1]
	v_pk_mul_f32 v[212:213], v[212:213], v[170:171] op_sel_hi:[1,0]
	v_pk_mul_f32 v[214:215], v[214:215], v[170:171] op_sel_hi:[1,0]
	v_pk_fma_f32 v[212:213], v[100:101], v[212:213], v[150:151]
	v_pk_fma_f32 v[214:215], v[102:103], v[214:215], v[152:153]
	v_pk_fma_f32 v[8:9], v[212:213], s[6:7], v[8:9] op_sel_hi:[1,0,1]
	v_pk_fma_f32 v[10:11], v[214:215], s[6:7], v[10:11] op_sel_hi:[1,0,1]
	global_store_dwordx4 v[230:231], v[8:11], off offset:64
	v_pk_mul_f32 v[4:5], v[4:5], v[92:93]
	v_pk_add_f32 v[216:217], v[216:217], v[128:129] op_sel_hi:[1,0] neg_lo:[0,1] neg_hi:[0,1]
	v_pk_mul_f32 v[6:7], v[6:7], v[94:95]
	v_pk_add_f32 v[218:219], v[218:219], v[128:129] op_sel_hi:[1,0] neg_lo:[0,1] neg_hi:[0,1]
	v_pk_mul_f32 v[216:217], v[216:217], v[170:171] op_sel_hi:[1,0]
	v_pk_mul_f32 v[218:219], v[218:219], v[170:171] op_sel_hi:[1,0]
	v_pk_fma_f32 v[216:217], v[104:105], v[216:217], v[142:143]
	v_pk_fma_f32 v[218:219], v[106:107], v[218:219], v[144:145]
	v_pk_fma_f32 v[4:5], v[216:217], s[6:7], v[4:5] op_sel_hi:[1,0,1]
	v_pk_fma_f32 v[6:7], v[218:219], s[6:7], v[6:7] op_sel_hi:[1,0,1]
	global_store_dwordx4 v[230:231], v[4:7], off offset:128
	v_pk_mul_f32 v[0:1], v[0:1], v[244:245]
	v_pk_add_f32 v[220:221], v[220:221], v[128:129] op_sel_hi:[1,0] neg_lo:[0,1] neg_hi:[0,1]
	v_pk_mul_f32 v[2:3], v[2:3], v[246:247]
	v_pk_add_f32 v[222:223], v[222:223], v[128:129] op_sel_hi:[1,0] neg_lo:[0,1] neg_hi:[0,1]
	v_pk_mul_f32 v[220:221], v[220:221], v[170:171] op_sel_hi:[1,0]
	v_pk_mul_f32 v[222:223], v[222:223], v[170:171] op_sel_hi:[1,0]
	v_pk_fma_f32 v[220:221], v[108:109], v[220:221], v[146:147]
	v_pk_fma_f32 v[222:223], v[110:111], v[222:223], v[148:149]
	v_pk_fma_f32 v[0:1], v[220:221], s[6:7], v[0:1] op_sel_hi:[1,0,1]
	v_pk_fma_f32 v[2:3], v[222:223], s[6:7], v[2:3] op_sel_hi:[1,0,1]
	global_store_dwordx4 v[230:231], v[0:3], off offset:192
.Lout_epi_done:
	v_readlane_b32 s12, v242, 25
	v_readlane_b32 s13, v242, 26
	v_readlane_b32 s14, v242, 27
	v_readlane_b32 s15, v242, 28
	v_readlane_b32 s16, v242, 29
	v_readlane_b32 s17, v242, 30
	v_readlane_b32 s18, v242, 31
	v_readlane_b32 s19, v242, 32
	v_readlane_b32 s20, v242, 33
	v_readlane_b32 s21, v242, 34
	v_readlane_b32 s22, v242, 35
	v_readlane_b32 s23, v242, 36
	v_readlane_b32 s24, v242, 37
	v_readlane_b32 s25, v242, 38
	v_readlane_b32 s26, v242, 39
	v_readlane_b32 s27, v242, 40
	s_mov_b64 s[10:11], 0x2000
	s_movk_i32 s4, 0xfff
	s_waitcnt lgkmcnt(0)
	s_barrier
	s_cmpk_gt_i32 s9, 0xff
	s_cbranch_scc0 .LBB0_127

.LBB0_575:
	v_readlane_b32 s0, v241, 18
	v_readlane_b32 s1, v241, 19
	s_andn2_b64 vcc, exec, s[0:1]
	s_cbranch_vccnz .LBB0_592
	v_ashrrev_i32_e32 v97, 6, v132
	v_readlane_b32 s0, v241, 20
	v_readlane_b32 s12, v242, 25
	v_and_b32_e32 v96, 63, v132
	s_waitcnt vmcnt(0)
	v_add_u32_e32 v0, s0, v97
	v_ashrrev_i32_e32 v1, 31, v0
	v_lshlrev_b64 v[0:1], 12, v[0:1]
	v_readlane_b32 s16, v242, 25
	v_readlane_b32 s17, v242, 26
	v_lshlrev_b32_e32 v128, 4, v96
	v_readlane_b32 s4, v241, 9
	v_lshl_add_u64 v[0:1], s[16:17], 0, v[0:1]
	v_lshl_add_u64 v[0:1], v[0:1], 0, v[128:129]
	global_load_dwordx4 v[48:51], v[0:1], off offset:3072
	global_load_dwordx4 v[52:55], v[0:1], off offset:2048
	global_load_dwordx4 v[56:59], v[0:1], off offset:1024
	global_load_dwordx4 v[60:63], v[0:1], off
	v_readlane_b32 s5, v241, 10
	s_sub_i32 s0, s4, 30
	v_readlane_b32 s4, v238, 23
	v_readlane_b32 s6, v241, 11
	s_cmp_gt_u32 s0, 8
	v_readlane_b32 s5, v238, 24
	v_readlane_b32 s13, v242, 26
	v_readlane_b32 s14, v242, 27
	v_readlane_b32 s15, v242, 28
	v_readlane_b32 s18, v242, 31
	v_readlane_b32 s19, v242, 32
	v_readlane_b32 s20, v242, 33
	v_readlane_b32 s21, v242, 34
	v_readlane_b32 s22, v242, 35
	v_readlane_b32 s23, v242, 36
	v_readlane_b32 s24, v242, 37
	v_readlane_b32 s25, v242, 38
	v_readlane_b32 s26, v242, 39
	v_readlane_b32 s27, v242, 40
	s_cselect_b64 s[0:1], -1, 0
	s_mov_b32 s10, s4
	s_min_i32 s6, s4, 2
	s_ashr_i32 s11, s4, 31
	v_writelane_b32 v238, s4, 23
	v_lshl_add_u64 v[98:99], s[16:17], 0, v[128:129]
	v_lshl_add_u64 v[100:101], s[12:13], 0, v[128:129]
	v_writelane_b32 v238, s5, 24
	s_lshl_b64 s[4:5], s[10:11], 12
	v_readlane_b32 s12, v242, 5
	v_readlane_b32 s7, v241, 12
	s_mul_i32 s9, s6, 3
	v_readlane_b32 s13, v242, 6
	v_readlane_b32 s14, v242, 7
	v_readlane_b32 s15, v242, 8
	v_readlane_b32 s16, v242, 9
	v_readlane_b32 s17, v242, 10
	v_readlane_b32 s18, v242, 11
	v_readlane_b32 s19, v242, 12
	v_readlane_b32 s20, v242, 13
	v_readlane_b32 s21, v242, 14
	v_readlane_b32 s22, v242, 15
	v_readlane_b32 s23, v242, 16
	v_readlane_b32 s24, v242, 17
	v_readlane_b32 s25, v242, 18
	v_readlane_b32 s26, v242, 19
	v_readlane_b32 s27, v242, 20
	s_add_u32 s6, s12, s4
	v_and_b32_e32 v0, 64, v191
	s_addc_u32 s7, s13, s5
	v_readlane_b32 s12, v243, 53
	v_xor_b32_e32 v1, 16, v191
	v_add_u32_e32 v9, 64, v0
	v_readlane_b32 s26, v242, 3
	v_xor_b32_e32 v5, 32, v191
	v_cmp_lt_i32_e32 vcc, v1, v9
	v_readlane_b32 s13, v243, 54
	v_readlane_b32 s14, v243, 55
	v_readlane_b32 s15, v243, 56
	v_readlane_b32 s16, v243, 57
	v_readlane_b32 s17, v243, 58
	v_readlane_b32 s18, v243, 59
	v_readlane_b32 s19, v243, 60
	v_readlane_b32 s20, v243, 61
	v_readlane_b32 s21, v243, 62
	v_readlane_b32 s22, v243, 63
	v_readlane_b32 s23, v242, 0
	v_readlane_b32 s24, v242, 1
	v_readlane_b32 s25, v242, 2
	v_readlane_b32 s27, v242, 4
	s_add_u32 s4, s26, s4
	v_cndmask_b32_e32 v1, v191, v1, vcc
	v_cmp_lt_i32_e32 vcc, v5, v9
	s_addc_u32 s5, s27, s5
	v_readlane_b32 s12, v242, 41
	v_or_b32_e32 v0, 64, v96
	v_or_b32_e32 v4, 0x80, v96
	v_or_b32_e32 v8, 0xc0, v96
	v_cndmask_b32_e32 v5, v191, v5, vcc
	v_lshl_add_u64 v[108:109], s[6:7], 0, v[128:129]
	v_lshl_add_u64 v[110:111], s[4:5], 0, v[128:129]
	v_lshlrev_b32_e32 v128, 3, v96
	v_readlane_b32 s14, v242, 43
	v_readlane_b32 s15, v242, 44
	s_waitcnt vmcnt(3)
	v_mov_b64_e32 v[32:33], v[48:49]
	s_waitcnt vmcnt(2)
	v_mov_b64_e32 v[36:37], v[52:53]
	s_waitcnt vmcnt(1)
	v_mov_b64_e32 v[40:41], v[56:57]
	s_waitcnt vmcnt(0)
	v_mov_b64_e32 v[44:45], v[60:61]
	v_readlane_b32 s8, v243, 0
	v_lshlrev_b32_e32 v102, 4, v0
	v_lshlrev_b32_e32 v104, 4, v4
	v_lshlrev_b32_e32 v106, 4, v8
	v_lshlrev_b32_e32 v122, 2, v1
	v_lshlrev_b32_e32 v123, 2, v5
	s_add_i32 s9, s9, 3
	v_lshl_add_u64 v[112:113], s[14:15], 0, v[128:129]
	v_mov_b64_e32 v[34:35], v[50:51]
	v_mov_b64_e32 v[38:39], v[54:55]
	v_mov_b64_e32 v[42:43], v[58:59]
	v_mov_b64_e32 v[46:47], v[62:63]
	v_readlane_b32 s13, v242, 42
	v_readlane_b32 s16, v242, 45
	v_readlane_b32 s17, v242, 46
	v_readlane_b32 s18, v242, 47
	v_readlane_b32 s19, v242, 48
	v_readlane_b32 s20, v242, 49
	v_readlane_b32 s21, v242, 50
	v_readlane_b32 s22, v242, 51
	v_readlane_b32 s23, v242, 52
	v_readlane_b32 s24, v242, 53
	v_readlane_b32 s25, v242, 54
	v_readlane_b32 s26, v242, 55
	v_readlane_b32 s27, v242, 56
	s_branch .LBB0_578

.LBB0_585:
	v_mov_b32_e32 v118, v60
	v_mov_b32_e32 v119, v56
	v_mov_b32_e32 v120, v61
	v_mov_b32_e32 v121, v57
	v_pk_add_f32 v[118:119], v[118:119], v[120:121]
	v_mov_b32_e32 v120, v62
	v_mov_b32_e32 v121, v58
	v_pk_add_f32 v[118:119], v[120:121], v[118:119]
	v_mov_b32_e32 v120, v63
	v_mov_b32_e32 v121, v59
	v_pk_add_f32 v[118:119], v[120:121], v[118:119]
	v_mov_b32_e32 v120, v53
	v_add_f32_e32 v103, 0, v118
	v_add_f32_e32 v103, v103, v119
	v_mov_b32_e32 v118, v52
	v_mov_b32_e32 v119, v48
	v_mov_b32_e32 v121, v49
	v_pk_add_f32 v[118:119], v[118:119], v[120:121]
	v_mov_b32_e32 v120, v54
	v_mov_b32_e32 v121, v50
	v_pk_add_f32 v[118:119], v[120:121], v[118:119]
	v_mov_b32_e32 v120, v55
	v_mov_b32_e32 v121, v51
	v_pk_add_f32 v[118:119], v[120:121], v[118:119]
	s_mov_b32 s6, 0x800000
	v_add_f32_e32 v103, v103, v118
	v_add_f32_e32 v103, v103, v119
	v_ashrrev_i32_e32 v117, 31, v116
	s_nop 0
	v_add_f32_dpp v103, v103, v103 quad_perm:[1,0,3,2] row_mask:0xf bank_mask:0xf bound_ctrl:1
	s_nop 1
	v_add_f32_dpp v103, v103, v103 quad_perm:[2,3,0,1] row_mask:0xf bank_mask:0xf bound_ctrl:1
	s_nop 1
	v_add_f32_dpp v103, v103, v103 row_half_mirror row_mask:0xf bank_mask:0xf bound_ctrl:1
	s_nop 1
	v_add_f32_dpp v103, v103, v103 row_mirror row_mask:0xf bank_mask:0xf bound_ctrl:1
	ds_bpermute_b32 v105, v122, v103
	s_waitcnt lgkmcnt(0)
	v_add_f32_e32 v103, v103, v105
	ds_bpermute_b32 v105, v123, v103
	s_waitcnt lgkmcnt(0)
	v_add_f32_e32 v103, v103, v105
	v_mul_f32_e32 v118, 0x3a800000, v103
	v_mov_b32_e32 v158, v118
	v_pk_add_f32 v[60:61], v[60:61], v[118:119] op_sel_hi:[1,0] neg_lo:[0,1] neg_hi:[0,1]
	v_pk_add_f32 v[56:57], v[56:57], v[118:119] op_sel_hi:[1,0] neg_lo:[0,1] neg_hi:[0,1]
	v_mov_b32_e32 v134, v61
	v_mov_b32_e32 v135, v57
	v_pk_add_f32 v[62:63], v[62:63], v[118:119] op_sel_hi:[1,0] neg_lo:[0,1] neg_hi:[0,1]
	v_pk_add_f32 v[58:59], v[58:59], v[118:119] op_sel_hi:[1,0] neg_lo:[0,1] neg_hi:[0,1]
	v_mov_b32_e32 v126, v60
	v_mov_b32_e32 v127, v56
	v_pk_mul_f32 v[134:135], v[134:135], v[134:135]
	v_mov_b32_e32 v120, v62
	v_mov_b32_e32 v121, v58
	v_pk_fma_f32 v[126:127], v[126:127], v[126:127], v[134:135]
	v_mov_b32_e32 v124, v63
	v_mov_b32_e32 v125, v59
	v_pk_fma_f32 v[120:121], v[120:121], v[120:121], v[126:127]
	v_pk_add_f32 v[126:127], v[52:53], v[118:119] op_sel_hi:[1,0] neg_lo:[0,1] neg_hi:[0,1]
	v_pk_fma_f32 v[120:121], v[124:125], v[124:125], v[120:121]
	v_pk_add_f32 v[124:125], v[54:55], v[118:119] op_sel_hi:[1,0] neg_lo:[0,1] neg_hi:[0,1]
	v_pk_add_f32 v[134:135], v[50:51], v[118:119] op_sel_hi:[1,0] neg_lo:[0,1] neg_hi:[0,1]
	v_pk_add_f32 v[118:119], v[48:49], v[118:119] op_sel_hi:[1,0] neg_lo:[0,1] neg_hi:[0,1]
	v_mov_b32_e32 v55, v127
	v_mov_b32_e32 v54, v119
	v_mov_b32_e32 v52, v118
	v_mov_b32_e32 v53, v126
	v_pk_mul_f32 v[54:55], v[54:55], v[54:55]
	v_mov_b32_e32 v48, v134
	v_mov_b32_e32 v49, v124
	v_pk_fma_f32 v[52:53], v[52:53], v[52:53], v[54:55]
	v_mov_b32_e32 v50, v135
	v_mov_b32_e32 v51, v125
	v_pk_fma_f32 v[48:49], v[48:49], v[48:49], v[52:53]
	s_nop 0
	v_pk_fma_f32 v[48:49], v[50:51], v[50:51], v[48:49]
	v_add_f32_e32 v50, v120, v121
	v_add_f32_e32 v49, v49, v50
	v_add_f32_e32 v48, v48, v49
	s_nop 1
	v_add_f32_dpp v48, v48, v48 quad_perm:[1,0,3,2] row_mask:0xf bank_mask:0xf bound_ctrl:1
	s_nop 1
	v_add_f32_dpp v48, v48, v48 quad_perm:[2,3,0,1] row_mask:0xf bank_mask:0xf bound_ctrl:1
	s_nop 1
	v_add_f32_dpp v48, v48, v48 row_half_mirror row_mask:0xf bank_mask:0xf bound_ctrl:1
	s_nop 1
	v_add_f32_dpp v48, v48, v48 row_mirror row_mask:0xf bank_mask:0xf bound_ctrl:1
	ds_bpermute_b32 v49, v122, v48
	s_waitcnt lgkmcnt(0)
	v_add_f32_e32 v48, v48, v49
	ds_bpermute_b32 v49, v123, v48
	s_waitcnt lgkmcnt(0)
	v_add_f32_e32 v48, v48, v49
	v_fmamk_f32 v48, v48, 0x3a800000, v177
	v_mul_f32_e32 v49, 0x4b800000, v48
	v_cmp_gt_f32_e32 vcc, s6, v48
	s_mov_b64 s[6:7], -1
	s_nop 0
	v_cndmask_b32_e32 v48, v48, v49, vcc
	v_rsq_f32_e32 v48, v48
	s_nop 0
	v_mul_f32_e32 v49, 0x45800000, v48
	v_cndmask_b32_e32 v120, v48, v49, vcc
	v_pk_mul_f32 v[50:51], v[62:63], v[120:121] op_sel_hi:[1,0]
	v_pk_mul_f32 v[48:49], v[60:61], v[120:121] op_sel_hi:[1,0]
	s_waitcnt vmcnt(6)
	v_pk_fma_f32 v[50:51], v[66:67], v[50:51], v[70:71]
	v_pk_mul_f32 v[52:53], v[56:57], v[120:121] op_sel_hi:[1,0]
	v_pk_mul_f32 v[54:55], v[58:59], v[120:121] op_sel_hi:[1,0]
	v_pk_mul_f32 v[56:57], v[126:127], v[120:121] op_sel_hi:[1,0]
	v_pk_mul_f32 v[58:59], v[124:125], v[120:121] op_sel_hi:[1,0]
	v_pk_mul_f32 v[60:61], v[118:119], v[120:121] op_sel_hi:[1,0]
	v_pk_mul_f32 v[62:63], v[134:135], v[120:121] op_sel_hi:[1,0]
	v_lshlrev_b64 v[66:67], 12, v[116:117]
	v_pk_fma_f32 v[48:49], v[64:65], v[48:49], v[68:69]
	s_waitcnt vmcnt(4)
	v_pk_fma_f32 v[52:53], v[72:73], v[52:53], v[76:77]
	v_pk_fma_f32 v[54:55], v[74:75], v[54:55], v[78:79]
	s_waitcnt vmcnt(2)
	v_pk_fma_f32 v[56:57], v[80:81], v[56:57], v[84:85]
	v_pk_fma_f32 v[58:59], v[82:83], v[58:59], v[86:87]
	s_waitcnt vmcnt(0)
	v_pk_fma_f32 v[60:61], v[88:89], v[60:61], v[92:93]
	v_pk_fma_f32 v[62:63], v[90:91], v[62:63], v[94:95]
	v_lshlrev_b64 v[64:65], 10, v[116:117]
	v_lshl_add_u64 v[66:67], v[100:101], 0, v[66:67]
	s_and_b64 vcc, exec, s[0:1]
	v_readlane_b32 s98, v243, 9
	v_readlane_b32 s99, v243, 10
	v_lshlrev_b64 v[160:161], 3, v[116:117]
	v_mov_b32_e32 v159, v120
	v_lshl_add_u64 v[160:161], s[98:99], 0, v[160:161]
	s_mov_b64 s[98:99], exec
	s_mov_b64 exec, 1
	global_store_dwordx2 v[160:161], v[158:159], off
	s_mov_b64 exec, s[98:99]
	s_cbranch_vccz .LBB0_587
	v_pk_add_f32 v[66:67], v[8:9], 1.0 op_sel_hi:[1,0]
	v_pk_add_f32 v[68:69], v[10:11], 1.0 op_sel_hi:[1,0]
	v_pk_fma_f32 v[66:67], v[66:67], v[48:49], v[0:1]
	v_pk_fma_f32 v[68:69], v[68:69], v[50:51], v[2:3]
	v_cvt_pk_bf16_f32 v66, v66, v67
	v_cvt_pk_bf16_f32 v67, v68, v69
	v_lshl_add_u64 v[68:69], v[64:65], 1, v[112:113]
	global_store_dwordx2 v[68:69], v[66:67], off
	v_pk_add_f32 v[66:67], v[16:17], 1.0 op_sel_hi:[1,0]
	v_pk_add_f32 v[70:71], v[18:19], 1.0 op_sel_hi:[1,0]
	v_pk_fma_f32 v[66:67], v[66:67], v[52:53], v[4:5]
	v_pk_fma_f32 v[70:71], v[70:71], v[54:55], v[6:7]
	v_cvt_pk_bf16_f32 v66, v66, v67
	v_cvt_pk_bf16_f32 v67, v70, v71
	global_store_dwordx2 v[68:69], v[66:67], off offset:512
	v_pk_add_f32 v[66:67], v[24:25], 1.0 op_sel_hi:[1,0]
	v_pk_add_f32 v[70:71], v[26:27], 1.0 op_sel_hi:[1,0]
	v_pk_fma_f32 v[66:67], v[66:67], v[56:57], v[12:13]
	v_pk_fma_f32 v[70:71], v[70:71], v[58:59], v[14:15]
	v_cvt_pk_bf16_f32 v66, v66, v67
	v_cvt_pk_bf16_f32 v67, v70, v71
	global_store_dwordx2 v[68:69], v[66:67], off offset:1024
	v_pk_add_f32 v[66:67], v[28:29], 1.0 op_sel_hi:[1,0]
	v_pk_add_f32 v[70:71], v[30:31], 1.0 op_sel_hi:[1,0]
	v_pk_fma_f32 v[66:67], v[66:67], v[60:61], v[20:21]
	v_pk_fma_f32 v[70:71], v[70:71], v[62:63], v[22:23]
	v_cvt_pk_bf16_f32 v66, v66, v67
	v_cvt_pk_bf16_f32 v67, v70, v71
	global_store_dwordx2 v[68:69], v[66:67], off offset:1536
	s_mov_b64 s[6:7], 0
